# hand-written pipelined RES, MERGE and STORE epilogues (prefetch rings, counted vmcnt); old MERGE/STORE epilogue code removed
# baseline (speedup 1.0000x reference)
; #define GAS __attribute__((address_space(1)))
; __device__ __forceinline__ u32x4 pack8(f32x4 a, f32x4 b) { u32x4 w; w.x = cvtpk(a[0], a[1]); w.y = cvtpk(a[2], a[3]); w.z = cvtpk(b[0], b[1]); w.w = cvtpk(b[2], b[3]); return w; }
; __device__ __forceinline__ f32x4 sig4(f32x4 x) { f32x4 r; r[0] = fsigmoid(x[0]); r[1] = fsigmoid(x[1]); r[2] = fsigmoid(x[2]); r[3] = fsigmoid(x[3]); return r; }
; __device__ __forceinline__ float dot4(f32x4 a) { return (a[0] * a[0] + a[1] * a[1]) + (a[2] * a[2] + a[3] * a[3]); }
;     __device__ __forceinline__ void operator()(const f32x4 (&acc)[2][2][4][2], const Unit& u, int wr, int wc, int fr, int fq) const {
;     ...
;         } else if (mode == EM_RES || mode == EM_PLE) {
; #pragma unroll
;             for (int ai = 0; ai < 2; ++ai)
; #pragma unroll
;                 for (int m = 0; m < 4; ++m) {
;                     const int row = rowb + ai * HALF + m * 16;
;                     float rstd = 1.f; if (mode == EM_PLE) rstd = __builtin_amdgcn_rsqf(ssq_in[row] * (1.0f / DM) + EPS);
;                     float ss = 0.f;
; #pragma unroll
;                     for (int bj = 0; bj < 2; ++bj) {
;                         const size_t off = (size_t)row * DM + u.pn * BM + bj * HALF + wc * 32 + fq * 8;
;                         f32x4 h0, h1, l0, l1; unpack8(*(const GAS u32x4*)(hin + off), h0, h1); unpack8(*(const GAS u32x4*)(lo + off), l0, l1);
;                         h0 += l0; h1 += l1;
;                         if (mode == EM_PLE) { f32x4 t0, t1; unpack8(*(const GAS u32x4*)(g16 + off), t0, t1);
;                             h0 += sig4(acc[ai][bj][m][0] * rstd) * t0; h1 += sig4(acc[ai][bj][m][1] * rstd) * t1; }
;                         else { h0 += acc[ai][bj][m][0] * scale; h1 += acc[ai][bj][m][1] * scale; }
;                         if (fin) { *(GAS f32x4*)(h + off) = h0; *(GAS f32x4*)(h + off + 4) = h1; }
;                         const u32x4 hw = pack8(h0, h1); f32x4 g0, g1; unpack8(hw, g0, g1);
;                         *(GAS u32x4*)(o16 + off) = hw;
;                         *(GAS u32x4*)(lo + off) = pack8(h0 - g0, h1 - g1);
;                         ss += dot4(h0) + dot4(h1);
;                     }
;                     ss += __shfl_xor(ss, 16); ss += __shfl_xor(ss, 32);
;                     if (fq == 0) (void)__hip_atomic_fetch_add(ssq_out + row, ss, __ATOMIC_RELAXED, __HIP_MEMORY_SCOPE_AGENT);
;                 }
.LBB0_409:
	s_and_b64 vcc, exec, s[78:79]
	s_cbranch_vccnz .Lres_fast
	v_cndmask_b32_e64 v130, 0, 1, s[78:79]
	v_cmp_ne_u32_e64 s[46:47], 1, v130
	s_andn2_b64 vcc, exec, s[78:79]
	s_mov_b64 s[0:1], -1
	s_cbranch_vccnz .LBB0_411
	v_ashrrev_i32_e32 v183, 31, v182
	s_mov_b64 s[0:1], 0

; #define GAS __attribute__((address_space(1)))
; __device__ __forceinline__ u32x4 pack8(f32x4 a, f32x4 b) { u32x4 w; w.x = cvtpk(a[0], a[1]); w.y = cvtpk(a[2], a[3]); w.z = cvtpk(b[0], b[1]); w.w = cvtpk(b[2], b[3]); return w; }
; __device__ __forceinline__ f32x4 sig4(f32x4 x) { f32x4 r; r[0] = fsigmoid(x[0]); r[1] = fsigmoid(x[1]); r[2] = fsigmoid(x[2]); r[3] = fsigmoid(x[3]); return r; }
; __device__ __forceinline__ float dot4(f32x4 a) { return (a[0] * a[0] + a[1] * a[1]) + (a[2] * a[2] + a[3] * a[3]); }
;     __device__ __forceinline__ void operator()(const f32x4 (&acc)[2][2][4][2], const Unit& u, int wr, int wc, int fr, int fq) const {
;     ...
;                     const int row = rowb + ai * HALF + m * 16;
;                     float rstd = 1.f; if (mode == EM_PLE) rstd = __builtin_amdgcn_rsqf(ssq_in[row] * (1.0f / DM) + EPS);
;                     float ss = 0.f;
; #pragma unroll
;                     for (int bj = 0; bj < 2; ++bj) {
;                         const size_t off = (size_t)row * DM + u.pn * BM + bj * HALF + wc * 32 + fq * 8;
;                         f32x4 h0, h1, l0, l1; unpack8(*(const GAS u32x4*)(hin + off), h0, h1); unpack8(*(const GAS u32x4*)(lo + off), l0, l1);
;                         h0 += l0; h1 += l1;
;                         if (mode == EM_PLE) { f32x4 t0, t1; unpack8(*(const GAS u32x4*)(g16 + off), t0, t1);
;                             h0 += sig4(acc[ai][bj][m][0] * rstd) * t0; h1 += sig4(acc[ai][bj][m][1] * rstd) * t1; }
;                         else { h0 += acc[ai][bj][m][0] * scale; h1 += acc[ai][bj][m][1] * scale; }
;                         if (fin) { *(GAS f32x4*)(h + off) = h0; *(GAS f32x4*)(h + off + 4) = h1; }
;                         const u32x4 hw = pack8(h0, h1); f32x4 g0, g1; unpack8(hw, g0, g1);
;                         *(GAS u32x4*)(o16 + off) = hw;
;                         *(GAS u32x4*)(lo + off) = pack8(h0 - g0, h1 - g1);
;                         ss += dot4(h0) + dot4(h1);
.Lres_fast:
	s_lshl_b32 s0, s67, 9
	v_lshlrev_b32_e32 v236, 11, v182
	v_lshl_add_u32 v236, v176, 1, v236
	v_add_u32_e32 v236, s0, v236
	v_lshlrev_b32_e32 v239, 2, v182
	v_mov_b32_e32 v237, v236
	global_load_dwordx4 v[132:135], v237, s[20:21]
	global_load_dwordx4 v[136:139], v237, s[64:65]
	global_load_dwordx4 v[140:143], v237, s[20:21] offset:256
	global_load_dwordx4 v[144:147], v237, s[64:65] offset:256
	v_add_u32_e32 v237, 0x8000, v236
	global_load_dwordx4 v[148:151], v237, s[20:21]
	global_load_dwordx4 v[152:155], v237, s[64:65]
	global_load_dwordx4 v[184:187], v237, s[20:21] offset:256
	global_load_dwordx4 v[188:191], v237, s[64:65] offset:256
	v_add_u32_e32 v237, 0x10000, v236
	global_load_dwordx4 v[192:195], v237, s[20:21]
	global_load_dwordx4 v[196:199], v237, s[64:65]
	global_load_dwordx4 v[200:203], v237, s[20:21] offset:256
	global_load_dwordx4 v[204:207], v237, s[64:65] offset:256
	v_pk_mul_f32 v[114:115], v[114:115], s[10:11]
	v_pk_mul_f32 v[116:117], v[116:117], s[90:91]
	v_pk_mul_f32 v[126:127], v[126:127], s[10:11]
	v_pk_mul_f32 v[128:129], v[128:129], s[90:91]
	v_mov_b32_e32 v238, v236
	s_waitcnt vmcnt(10)
	v_lshlrev_b32_e32 v218, 16, v132
	v_and_b32_e32 v219, 0xffff0000, v132
	v_lshlrev_b32_e32 v220, 16, v133
	v_and_b32_e32 v221, 0xffff0000, v133
	v_lshlrev_b32_e32 v222, 16, v134
	v_and_b32_e32 v223, 0xffff0000, v134
	v_lshlrev_b32_e32 v224, 16, v135
	v_and_b32_e32 v225, 0xffff0000, v135
	v_lshlrev_b32_e32 v226, 16, v136
	v_and_b32_e32 v227, 0xffff0000, v136
	v_lshlrev_b32_e32 v228, 16, v137
	v_and_b32_e32 v229, 0xffff0000, v137
	v_lshlrev_b32_e32 v230, 16, v138
	v_and_b32_e32 v231, 0xffff0000, v138
	v_lshlrev_b32_e32 v232, 16, v139
	v_and_b32_e32 v233, 0xffff0000, v139
	v_add_u32_e32 v237, 0x18000, v236
	global_load_dwordx4 v[132:135], v237, s[20:21]
	global_load_dwordx4 v[136:139], v237, s[64:65]
	v_pk_add_f32 v[218:219], v[218:219], v[226:227]
	v_pk_add_f32 v[220:221], v[220:221], v[228:229]
	v_pk_add_f32 v[222:223], v[222:223], v[230:231]
	v_pk_add_f32 v[224:225], v[224:225], v[232:233]
	v_pk_add_f32 v[114:115], v[218:219], v[114:115]
	v_pk_add_f32 v[116:117], v[220:221], v[116:117]
	v_pk_add_f32 v[126:127], v[222:223], v[126:127]
	v_pk_add_f32 v[128:129], v[224:225], v[128:129]
	v_pk_mul_f32 v[234:235], v[114:115], v[114:115]
	v_pk_fma_f32 v[234:235], v[116:117], v[116:117], v[234:235]
	v_pk_fma_f32 v[234:235], v[126:127], v[126:127], v[234:235]
	v_pk_fma_f32 v[234:235], v[128:129], v[128:129], v[234:235]
	v_cvt_pk_bf16_f32 v226, v114, v115
	v_cvt_pk_bf16_f32 v227, v116, v117
	v_cvt_pk_bf16_f32 v228, v126, v127
	v_cvt_pk_bf16_f32 v229, v128, v129
	global_store_dwordx4 v238, v[226:229], s[18:19]
	v_lshlrev_b32_e32 v218, 16, v226
	v_and_b32_e32 v219, 0xffff0000, v226
	v_lshlrev_b32_e32 v220, 16, v227
	v_and_b32_e32 v221, 0xffff0000, v227
	v_lshlrev_b32_e32 v222, 16, v228
	v_and_b32_e32 v223, 0xffff0000, v228
	v_lshlrev_b32_e32 v224, 16, v229
	v_and_b32_e32 v225, 0xffff0000, v229
	v_pk_add_f32 v[218:219], v[114:115], v[218:219] neg_lo:[0,1] neg_hi:[0,1]
	v_pk_add_f32 v[220:221], v[116:117], v[220:221] neg_lo:[0,1] neg_hi:[0,1]
	v_pk_add_f32 v[222:223], v[126:127], v[222:223] neg_lo:[0,1] neg_hi:[0,1]
	v_pk_add_f32 v[224:225], v[128:129], v[224:225] neg_lo:[0,1] neg_hi:[0,1]
	v_cvt_pk_bf16_f32 v230, v218, v219
	v_cvt_pk_bf16_f32 v231, v220, v221
	v_cvt_pk_bf16_f32 v232, v222, v223
	v_cvt_pk_bf16_f32 v233, v224, v225
	global_store_dwordx4 v238, v[230:233], s[64:65]
	v_pk_mul_f32 v[122:123], v[122:123], s[10:11]
	v_pk_mul_f32 v[124:125], v[124:125], s[90:91]
	v_pk_mul_f32 v[118:119], v[118:119], s[10:11]
	v_pk_mul_f32 v[120:121], v[120:121], s[90:91]
	s_waitcnt vmcnt(12)
	v_lshlrev_b32_e32 v218, 16, v140
	v_and_b32_e32 v219, 0xffff0000, v140
	v_lshlrev_b32_e32 v220, 16, v141
	v_and_b32_e32 v221, 0xffff0000, v141
	v_lshlrev_b32_e32 v222, 16, v142
	v_and_b32_e32 v223, 0xffff0000, v142
	v_lshlrev_b32_e32 v224, 16, v143
	v_and_b32_e32 v225, 0xffff0000, v143
	v_lshlrev_b32_e32 v226, 16, v144
	v_and_b32_e32 v227, 0xffff0000, v144
	v_lshlrev_b32_e32 v228, 16, v145
	v_and_b32_e32 v229, 0xffff0000, v145
	v_lshlrev_b32_e32 v230, 16, v146
	v_and_b32_e32 v231, 0xffff0000, v146
	v_lshlrev_b32_e32 v232, 16, v147
	v_and_b32_e32 v233, 0xffff0000, v147
	global_load_dwordx4 v[140:143], v237, s[20:21] offset:256
	global_load_dwordx4 v[144:147], v237, s[64:65] offset:256
	v_pk_add_f32 v[218:219], v[218:219], v[226:227]
	v_pk_add_f32 v[220:221], v[220:221], v[228:229]
	v_pk_add_f32 v[222:223], v[222:223], v[230:231]
	v_pk_add_f32 v[224:225], v[224:225], v[232:233]
	v_pk_add_f32 v[122:123], v[218:219], v[122:123]
	v_pk_add_f32 v[124:125], v[220:221], v[124:125]
	v_pk_add_f32 v[118:119], v[222:223], v[118:119]
	v_pk_add_f32 v[120:121], v[224:225], v[120:121]
	v_pk_fma_f32 v[234:235], v[122:123], v[122:123], v[234:235]
	v_pk_fma_f32 v[234:235], v[124:125], v[124:125], v[234:235]
	v_pk_fma_f32 v[234:235], v[118:119], v[118:119], v[234:235]
	v_pk_fma_f32 v[234:235], v[120:121], v[120:121], v[234:235]
	v_cvt_pk_bf16_f32 v226, v122, v123
	v_cvt_pk_bf16_f32 v227, v124, v125
	v_cvt_pk_bf16_f32 v228, v118, v119
	v_cvt_pk_bf16_f32 v229, v120, v121
	global_store_dwordx4 v238, v[226:229], s[18:19] offset:256
	v_lshlrev_b32_e32 v218, 16, v226
	v_and_b32_e32 v219, 0xffff0000, v226
	v_lshlrev_b32_e32 v220, 16, v227
	v_and_b32_e32 v221, 0xffff0000, v227
	v_lshlrev_b32_e32 v222, 16, v228
	v_and_b32_e32 v223, 0xffff0000, v228
	v_lshlrev_b32_e32 v224, 16, v229
	v_and_b32_e32 v225, 0xffff0000, v229
	v_pk_add_f32 v[218:219], v[122:123], v[218:219] neg_lo:[0,1] neg_hi:[0,1]
	v_pk_add_f32 v[220:221], v[124:125], v[220:221] neg_lo:[0,1] neg_hi:[0,1]
	v_pk_add_f32 v[222:223], v[118:119], v[222:223] neg_lo:[0,1] neg_hi:[0,1]
	v_pk_add_f32 v[224:225], v[120:121], v[224:225] neg_lo:[0,1] neg_hi:[0,1]
	v_cvt_pk_bf16_f32 v230, v218, v219
	v_cvt_pk_bf16_f32 v231, v220, v221
	v_cvt_pk_bf16_f32 v232, v222, v223
	v_cvt_pk_bf16_f32 v233, v224, v225
	global_store_dwordx4 v238, v[230:233], s[64:65] offset:256
	v_add_f32_e32 v114, v234, v235
	v_pk_mul_f32 v[110:111], v[110:111], s[10:11]
	v_pk_mul_f32 v[112:113], v[112:113], s[90:91]
	v_pk_mul_f32 v[102:103], v[102:103], s[10:11]
	v_pk_mul_f32 v[104:105], v[104:105], s[90:91]
	v_add_u32_e32 v238, 0x8000, v236
	s_waitcnt vmcnt(14)
; #define GAS __attribute__((address_space(1)))
; __device__ __forceinline__ u32x4 pack8(f32x4 a, f32x4 b) { u32x4 w; w.x = cvtpk(a[0], a[1]); w.y = cvtpk(a[2], a[3]); w.z = cvtpk(b[0], b[1]); w.w = cvtpk(b[2], b[3]); return w; }
; __device__ __forceinline__ f32x4 sig4(f32x4 x) { f32x4 r; r[0] = fsigmoid(x[0]); r[1] = fsigmoid(x[1]); r[2] = fsigmoid(x[2]); r[3] = fsigmoid(x[3]); return r; }
; __device__ __forceinline__ float dot4(f32x4 a) { return (a[0] * a[0] + a[1] * a[1]) + (a[2] * a[2] + a[3] * a[3]); }
;     __device__ __forceinline__ void operator()(const f32x4 (&acc)[2][2][4][2], const Unit& u, int wr, int wc, int fr, int fq) const {
;     ...
;                     const int row = rowb + ai * HALF + m * 16;
;                     float rstd = 1.f; if (mode == EM_PLE) rstd = __builtin_amdgcn_rsqf(ssq_in[row] * (1.0f / DM) + EPS);
;                     float ss = 0.f;
; #pragma unroll
;                     for (int bj = 0; bj < 2; ++bj) {
;                         const size_t off = (size_t)row * DM + u.pn * BM + bj * HALF + wc * 32 + fq * 8;
;                         f32x4 h0, h1, l0, l1; unpack8(*(const GAS u32x4*)(hin + off), h0, h1); unpack8(*(const GAS u32x4*)(lo + off), l0, l1);
;                         h0 += l0; h1 += l1;
;                         if (mode == EM_PLE) { f32x4 t0, t1; unpack8(*(const GAS u32x4*)(g16 + off), t0, t1);
;                             h0 += sig4(acc[ai][bj][m][0] * rstd) * t0; h1 += sig4(acc[ai][bj][m][1] * rstd) * t1; }
;                         else { h0 += acc[ai][bj][m][0] * scale; h1 += acc[ai][bj][m][1] * scale; }
;                         if (fin) { *(GAS f32x4*)(h + off) = h0; *(GAS f32x4*)(h + off + 4) = h1; }
;                         const u32x4 hw = pack8(h0, h1); f32x4 g0, g1; unpack8(hw, g0, g1);
;                         *(GAS u32x4*)(o16 + off) = hw;
;                         *(GAS u32x4*)(lo + off) = pack8(h0 - g0, h1 - g1);
;                         ss += dot4(h0) + dot4(h1);
	v_lshlrev_b32_e32 v218, 16, v148
	v_and_b32_e32 v219, 0xffff0000, v148
	v_lshlrev_b32_e32 v220, 16, v149
	v_and_b32_e32 v221, 0xffff0000, v149
	v_lshlrev_b32_e32 v222, 16, v150
	v_and_b32_e32 v223, 0xffff0000, v150
	v_lshlrev_b32_e32 v224, 16, v151
	v_and_b32_e32 v225, 0xffff0000, v151
	v_lshlrev_b32_e32 v226, 16, v152
	v_and_b32_e32 v227, 0xffff0000, v152
	v_lshlrev_b32_e32 v228, 16, v153
	v_and_b32_e32 v229, 0xffff0000, v153
	v_lshlrev_b32_e32 v230, 16, v154
	v_and_b32_e32 v231, 0xffff0000, v154
	v_lshlrev_b32_e32 v232, 16, v155
	v_and_b32_e32 v233, 0xffff0000, v155
	v_add_u32_e32 v237, 0x40000, v236
	global_load_dwordx4 v[148:151], v237, s[20:21]
	global_load_dwordx4 v[152:155], v237, s[64:65]
	v_pk_add_f32 v[218:219], v[218:219], v[226:227]
	v_pk_add_f32 v[220:221], v[220:221], v[228:229]
	v_pk_add_f32 v[222:223], v[222:223], v[230:231]
	v_pk_add_f32 v[224:225], v[224:225], v[232:233]
	v_pk_add_f32 v[110:111], v[218:219], v[110:111]
	v_pk_add_f32 v[112:113], v[220:221], v[112:113]
	v_pk_add_f32 v[102:103], v[222:223], v[102:103]
	v_pk_add_f32 v[104:105], v[224:225], v[104:105]
	v_pk_mul_f32 v[234:235], v[110:111], v[110:111]
	v_pk_fma_f32 v[234:235], v[112:113], v[112:113], v[234:235]
	v_pk_fma_f32 v[234:235], v[102:103], v[102:103], v[234:235]
	v_pk_fma_f32 v[234:235], v[104:105], v[104:105], v[234:235]
	v_cvt_pk_bf16_f32 v226, v110, v111
	v_cvt_pk_bf16_f32 v227, v112, v113
	v_cvt_pk_bf16_f32 v228, v102, v103
	v_cvt_pk_bf16_f32 v229, v104, v105
	global_store_dwordx4 v238, v[226:229], s[18:19]
	v_lshlrev_b32_e32 v218, 16, v226
	v_and_b32_e32 v219, 0xffff0000, v226
	v_lshlrev_b32_e32 v220, 16, v227
	v_and_b32_e32 v221, 0xffff0000, v227
	v_lshlrev_b32_e32 v222, 16, v228
	v_and_b32_e32 v223, 0xffff0000, v228
	v_lshlrev_b32_e32 v224, 16, v229
	v_and_b32_e32 v225, 0xffff0000, v229
	v_pk_add_f32 v[218:219], v[110:111], v[218:219] neg_lo:[0,1] neg_hi:[0,1]
	v_pk_add_f32 v[220:221], v[112:113], v[220:221] neg_lo:[0,1] neg_hi:[0,1]
	v_pk_add_f32 v[222:223], v[102:103], v[222:223] neg_lo:[0,1] neg_hi:[0,1]
	v_pk_add_f32 v[224:225], v[104:105], v[224:225] neg_lo:[0,1] neg_hi:[0,1]
	v_cvt_pk_bf16_f32 v230, v218, v219
	v_cvt_pk_bf16_f32 v231, v220, v221
	v_cvt_pk_bf16_f32 v232, v222, v223
	v_cvt_pk_bf16_f32 v233, v224, v225
	global_store_dwordx4 v238, v[230:233], s[64:65]
	v_pk_mul_f32 v[106:107], v[106:107], s[10:11]
	v_pk_mul_f32 v[108:109], v[108:109], s[90:91]
	v_pk_mul_f32 v[98:99], v[98:99], s[10:11]
	v_pk_mul_f32 v[100:101], v[100:101], s[90:91]
	s_waitcnt vmcnt(16)
	v_lshlrev_b32_e32 v218, 16, v184
	v_and_b32_e32 v219, 0xffff0000, v184
	v_lshlrev_b32_e32 v220, 16, v185
	v_and_b32_e32 v221, 0xffff0000, v185
	v_lshlrev_b32_e32 v222, 16, v186
	v_and_b32_e32 v223, 0xffff0000, v186
	v_lshlrev_b32_e32 v224, 16, v187
	v_and_b32_e32 v225, 0xffff0000, v187
	v_lshlrev_b32_e32 v226, 16, v188
	v_and_b32_e32 v227, 0xffff0000, v188
	v_lshlrev_b32_e32 v228, 16, v189
	v_and_b32_e32 v229, 0xffff0000, v189
	v_lshlrev_b32_e32 v230, 16, v190
	v_and_b32_e32 v231, 0xffff0000, v190
	v_lshlrev_b32_e32 v232, 16, v191
	v_and_b32_e32 v233, 0xffff0000, v191
	global_load_dwordx4 v[184:187], v237, s[20:21] offset:256
	global_load_dwordx4 v[188:191], v237, s[64:65] offset:256
	v_pk_add_f32 v[218:219], v[218:219], v[226:227]
	v_pk_add_f32 v[220:221], v[220:221], v[228:229]
	v_pk_add_f32 v[222:223], v[222:223], v[230:231]
	v_pk_add_f32 v[224:225], v[224:225], v[232:233]
	v_pk_add_f32 v[106:107], v[218:219], v[106:107]
	v_pk_add_f32 v[108:109], v[220:221], v[108:109]
	v_pk_add_f32 v[98:99], v[222:223], v[98:99]
	v_pk_add_f32 v[100:101], v[224:225], v[100:101]
	v_pk_fma_f32 v[234:235], v[106:107], v[106:107], v[234:235]
	v_pk_fma_f32 v[234:235], v[108:109], v[108:109], v[234:235]
	v_pk_fma_f32 v[234:235], v[98:99], v[98:99], v[234:235]
	v_pk_fma_f32 v[234:235], v[100:101], v[100:101], v[234:235]
	v_cvt_pk_bf16_f32 v226, v106, v107
	v_cvt_pk_bf16_f32 v227, v108, v109
	v_cvt_pk_bf16_f32 v228, v98, v99
	v_cvt_pk_bf16_f32 v229, v100, v101
	global_store_dwordx4 v238, v[226:229], s[18:19] offset:256
	v_lshlrev_b32_e32 v218, 16, v226
	v_and_b32_e32 v219, 0xffff0000, v226
	v_lshlrev_b32_e32 v220, 16, v227
	v_and_b32_e32 v221, 0xffff0000, v227
	v_lshlrev_b32_e32 v222, 16, v228
	v_and_b32_e32 v223, 0xffff0000, v228
	v_lshlrev_b32_e32 v224, 16, v229
	v_and_b32_e32 v225, 0xffff0000, v229
	v_pk_add_f32 v[218:219], v[106:107], v[218:219] neg_lo:[0,1] neg_hi:[0,1]
	v_pk_add_f32 v[220:221], v[108:109], v[220:221] neg_lo:[0,1] neg_hi:[0,1]
	v_pk_add_f32 v[222:223], v[98:99], v[222:223] neg_lo:[0,1] neg_hi:[0,1]
	v_pk_add_f32 v[224:225], v[100:101], v[224:225] neg_lo:[0,1] neg_hi:[0,1]
	v_cvt_pk_bf16_f32 v230, v218, v219
	v_cvt_pk_bf16_f32 v231, v220, v221
	v_cvt_pk_bf16_f32 v232, v222, v223
	v_cvt_pk_bf16_f32 v233, v224, v225
	global_store_dwordx4 v238, v[230:233], s[64:65] offset:256
	v_add_f32_e32 v110, v234, v235
	v_pk_mul_f32 v[94:95], v[94:95], s[10:11]
	v_pk_mul_f32 v[96:97], v[96:97], s[90:91]
	v_pk_mul_f32 v[86:87], v[86:87], s[10:11]
	v_pk_mul_f32 v[88:89], v[88:89], s[90:91]
	v_add_u32_e32 v238, 0x10000, v236
	s_waitcnt vmcnt(18)
; #define GAS __attribute__((address_space(1)))
; __device__ __forceinline__ u32x4 pack8(f32x4 a, f32x4 b) { u32x4 w; w.x = cvtpk(a[0], a[1]); w.y = cvtpk(a[2], a[3]); w.z = cvtpk(b[0], b[1]); w.w = cvtpk(b[2], b[3]); return w; }
; __device__ __forceinline__ f32x4 sig4(f32x4 x) { f32x4 r; r[0] = fsigmoid(x[0]); r[1] = fsigmoid(x[1]); r[2] = fsigmoid(x[2]); r[3] = fsigmoid(x[3]); return r; }
; __device__ __forceinline__ float dot4(f32x4 a) { return (a[0] * a[0] + a[1] * a[1]) + (a[2] * a[2] + a[3] * a[3]); }
;     __device__ __forceinline__ void operator()(const f32x4 (&acc)[2][2][4][2], const Unit& u, int wr, int wc, int fr, int fq) const {
;     ...
;                     const int row = rowb + ai * HALF + m * 16;
;                     float rstd = 1.f; if (mode == EM_PLE) rstd = __builtin_amdgcn_rsqf(ssq_in[row] * (1.0f / DM) + EPS);
;                     float ss = 0.f;
; #pragma unroll
;                     for (int bj = 0; bj < 2; ++bj) {
;                         const size_t off = (size_t)row * DM + u.pn * BM + bj * HALF + wc * 32 + fq * 8;
;                         f32x4 h0, h1, l0, l1; unpack8(*(const GAS u32x4*)(hin + off), h0, h1); unpack8(*(const GAS u32x4*)(lo + off), l0, l1);
;                         h0 += l0; h1 += l1;
;                         if (mode == EM_PLE) { f32x4 t0, t1; unpack8(*(const GAS u32x4*)(g16 + off), t0, t1);
;                             h0 += sig4(acc[ai][bj][m][0] * rstd) * t0; h1 += sig4(acc[ai][bj][m][1] * rstd) * t1; }
;                         else { h0 += acc[ai][bj][m][0] * scale; h1 += acc[ai][bj][m][1] * scale; }
;                         if (fin) { *(GAS f32x4*)(h + off) = h0; *(GAS f32x4*)(h + off + 4) = h1; }
;                         const u32x4 hw = pack8(h0, h1); f32x4 g0, g1; unpack8(hw, g0, g1);
;                         *(GAS u32x4*)(o16 + off) = hw;
;                         *(GAS u32x4*)(lo + off) = pack8(h0 - g0, h1 - g1);
;                         ss += dot4(h0) + dot4(h1);
	v_lshlrev_b32_e32 v218, 16, v192
	v_and_b32_e32 v219, 0xffff0000, v192
	v_lshlrev_b32_e32 v220, 16, v193
	v_and_b32_e32 v221, 0xffff0000, v193
	v_lshlrev_b32_e32 v222, 16, v194
	v_and_b32_e32 v223, 0xffff0000, v194
	v_lshlrev_b32_e32 v224, 16, v195
	v_and_b32_e32 v225, 0xffff0000, v195
	v_lshlrev_b32_e32 v226, 16, v196
	v_and_b32_e32 v227, 0xffff0000, v196
	v_lshlrev_b32_e32 v228, 16, v197
	v_and_b32_e32 v229, 0xffff0000, v197
	v_lshlrev_b32_e32 v230, 16, v198
	v_and_b32_e32 v231, 0xffff0000, v198
	v_lshlrev_b32_e32 v232, 16, v199
	v_and_b32_e32 v233, 0xffff0000, v199
	v_add_u32_e32 v237, 0x48000, v236
	global_load_dwordx4 v[192:195], v237, s[20:21]
	global_load_dwordx4 v[196:199], v237, s[64:65]
	v_pk_add_f32 v[218:219], v[218:219], v[226:227]
	v_pk_add_f32 v[220:221], v[220:221], v[228:229]
	v_pk_add_f32 v[222:223], v[222:223], v[230:231]
	v_pk_add_f32 v[224:225], v[224:225], v[232:233]
	v_pk_add_f32 v[94:95], v[218:219], v[94:95]
	v_pk_add_f32 v[96:97], v[220:221], v[96:97]
	v_pk_add_f32 v[86:87], v[222:223], v[86:87]
	v_pk_add_f32 v[88:89], v[224:225], v[88:89]
	v_pk_mul_f32 v[234:235], v[94:95], v[94:95]
	v_pk_fma_f32 v[234:235], v[96:97], v[96:97], v[234:235]
	v_pk_fma_f32 v[234:235], v[86:87], v[86:87], v[234:235]
	v_pk_fma_f32 v[234:235], v[88:89], v[88:89], v[234:235]
	v_cvt_pk_bf16_f32 v226, v94, v95
	v_cvt_pk_bf16_f32 v227, v96, v97
	v_cvt_pk_bf16_f32 v228, v86, v87
	v_cvt_pk_bf16_f32 v229, v88, v89
	global_store_dwordx4 v238, v[226:229], s[18:19]
	v_lshlrev_b32_e32 v218, 16, v226
	v_and_b32_e32 v219, 0xffff0000, v226
	v_lshlrev_b32_e32 v220, 16, v227
	v_and_b32_e32 v221, 0xffff0000, v227
	v_lshlrev_b32_e32 v222, 16, v228
	v_and_b32_e32 v223, 0xffff0000, v228
	v_lshlrev_b32_e32 v224, 16, v229
	v_and_b32_e32 v225, 0xffff0000, v229
	v_pk_add_f32 v[218:219], v[94:95], v[218:219] neg_lo:[0,1] neg_hi:[0,1]
	v_pk_add_f32 v[220:221], v[96:97], v[220:221] neg_lo:[0,1] neg_hi:[0,1]
	v_pk_add_f32 v[222:223], v[86:87], v[222:223] neg_lo:[0,1] neg_hi:[0,1]
	v_pk_add_f32 v[224:225], v[88:89], v[224:225] neg_lo:[0,1] neg_hi:[0,1]
	v_cvt_pk_bf16_f32 v230, v218, v219
	v_cvt_pk_bf16_f32 v231, v220, v221
	v_cvt_pk_bf16_f32 v232, v222, v223
	v_cvt_pk_bf16_f32 v233, v224, v225
	global_store_dwordx4 v238, v[230:233], s[64:65]
	v_pk_mul_f32 v[90:91], v[90:91], s[10:11]
	v_pk_mul_f32 v[92:93], v[92:93], s[90:91]
	v_pk_mul_f32 v[82:83], v[82:83], s[10:11]
	v_pk_mul_f32 v[84:85], v[84:85], s[90:91]
	s_waitcnt vmcnt(20)
	v_lshlrev_b32_e32 v218, 16, v200
	v_and_b32_e32 v219, 0xffff0000, v200
	v_lshlrev_b32_e32 v220, 16, v201
	v_and_b32_e32 v221, 0xffff0000, v201
	v_lshlrev_b32_e32 v222, 16, v202
	v_and_b32_e32 v223, 0xffff0000, v202
	v_lshlrev_b32_e32 v224, 16, v203
	v_and_b32_e32 v225, 0xffff0000, v203
	v_lshlrev_b32_e32 v226, 16, v204
	v_and_b32_e32 v227, 0xffff0000, v204
	v_lshlrev_b32_e32 v228, 16, v205
	v_and_b32_e32 v229, 0xffff0000, v205
	v_lshlrev_b32_e32 v230, 16, v206
	v_and_b32_e32 v231, 0xffff0000, v206
	v_lshlrev_b32_e32 v232, 16, v207
	v_and_b32_e32 v233, 0xffff0000, v207
	global_load_dwordx4 v[200:203], v237, s[20:21] offset:256
	global_load_dwordx4 v[204:207], v237, s[64:65] offset:256
	v_pk_add_f32 v[218:219], v[218:219], v[226:227]
	v_pk_add_f32 v[220:221], v[220:221], v[228:229]
	v_pk_add_f32 v[222:223], v[222:223], v[230:231]
	v_pk_add_f32 v[224:225], v[224:225], v[232:233]
	v_pk_add_f32 v[90:91], v[218:219], v[90:91]
	v_pk_add_f32 v[92:93], v[220:221], v[92:93]
	v_pk_add_f32 v[82:83], v[222:223], v[82:83]
	v_pk_add_f32 v[84:85], v[224:225], v[84:85]
	v_pk_fma_f32 v[234:235], v[90:91], v[90:91], v[234:235]
	v_pk_fma_f32 v[234:235], v[92:93], v[92:93], v[234:235]
	v_pk_fma_f32 v[234:235], v[82:83], v[82:83], v[234:235]
	v_pk_fma_f32 v[234:235], v[84:85], v[84:85], v[234:235]
	v_cvt_pk_bf16_f32 v226, v90, v91
	v_cvt_pk_bf16_f32 v227, v92, v93
	v_cvt_pk_bf16_f32 v228, v82, v83
	v_cvt_pk_bf16_f32 v229, v84, v85
	global_store_dwordx4 v238, v[226:229], s[18:19] offset:256
	v_lshlrev_b32_e32 v218, 16, v226
	v_and_b32_e32 v219, 0xffff0000, v226
	v_lshlrev_b32_e32 v220, 16, v227
	v_and_b32_e32 v221, 0xffff0000, v227
	v_lshlrev_b32_e32 v222, 16, v228
	v_and_b32_e32 v223, 0xffff0000, v228
	v_lshlrev_b32_e32 v224, 16, v229
	v_and_b32_e32 v225, 0xffff0000, v229
	v_pk_add_f32 v[218:219], v[90:91], v[218:219] neg_lo:[0,1] neg_hi:[0,1]
	v_pk_add_f32 v[220:221], v[92:93], v[220:221] neg_lo:[0,1] neg_hi:[0,1]
	v_pk_add_f32 v[222:223], v[82:83], v[222:223] neg_lo:[0,1] neg_hi:[0,1]
	v_pk_add_f32 v[224:225], v[84:85], v[224:225] neg_lo:[0,1] neg_hi:[0,1]
	v_cvt_pk_bf16_f32 v230, v218, v219
	v_cvt_pk_bf16_f32 v231, v220, v221
	v_cvt_pk_bf16_f32 v232, v222, v223
	v_cvt_pk_bf16_f32 v233, v224, v225
	global_store_dwordx4 v238, v[230:233], s[64:65] offset:256
	v_add_f32_e32 v94, v234, v235
	v_pk_mul_f32 v[78:79], v[78:79], s[10:11]
	v_pk_mul_f32 v[80:81], v[80:81], s[90:91]
	v_pk_mul_f32 v[70:71], v[70:71], s[10:11]
	v_pk_mul_f32 v[72:73], v[72:73], s[90:91]
	v_add_u32_e32 v238, 0x18000, v236
	s_waitcnt vmcnt(22)
; #define GAS __attribute__((address_space(1)))
; __device__ __forceinline__ u32x4 pack8(f32x4 a, f32x4 b) { u32x4 w; w.x = cvtpk(a[0], a[1]); w.y = cvtpk(a[2], a[3]); w.z = cvtpk(b[0], b[1]); w.w = cvtpk(b[2], b[3]); return w; }
; __device__ __forceinline__ f32x4 sig4(f32x4 x) { f32x4 r; r[0] = fsigmoid(x[0]); r[1] = fsigmoid(x[1]); r[2] = fsigmoid(x[2]); r[3] = fsigmoid(x[3]); return r; }
; __device__ __forceinline__ float dot4(f32x4 a) { return (a[0] * a[0] + a[1] * a[1]) + (a[2] * a[2] + a[3] * a[3]); }
;     __device__ __forceinline__ void operator()(const f32x4 (&acc)[2][2][4][2], const Unit& u, int wr, int wc, int fr, int fq) const {
;     ...
;                     const int row = rowb + ai * HALF + m * 16;
;                     float rstd = 1.f; if (mode == EM_PLE) rstd = __builtin_amdgcn_rsqf(ssq_in[row] * (1.0f / DM) + EPS);
;                     float ss = 0.f;
; #pragma unroll
;                     for (int bj = 0; bj < 2; ++bj) {
;                         const size_t off = (size_t)row * DM + u.pn * BM + bj * HALF + wc * 32 + fq * 8;
;                         f32x4 h0, h1, l0, l1; unpack8(*(const GAS u32x4*)(hin + off), h0, h1); unpack8(*(const GAS u32x4*)(lo + off), l0, l1);
;                         h0 += l0; h1 += l1;
;                         if (mode == EM_PLE) { f32x4 t0, t1; unpack8(*(const GAS u32x4*)(g16 + off), t0, t1);
;                             h0 += sig4(acc[ai][bj][m][0] * rstd) * t0; h1 += sig4(acc[ai][bj][m][1] * rstd) * t1; }
;                         else { h0 += acc[ai][bj][m][0] * scale; h1 += acc[ai][bj][m][1] * scale; }
;                         if (fin) { *(GAS f32x4*)(h + off) = h0; *(GAS f32x4*)(h + off + 4) = h1; }
;                         const u32x4 hw = pack8(h0, h1); f32x4 g0, g1; unpack8(hw, g0, g1);
;                         *(GAS u32x4*)(o16 + off) = hw;
;                         *(GAS u32x4*)(lo + off) = pack8(h0 - g0, h1 - g1);
;                         ss += dot4(h0) + dot4(h1);
	v_lshlrev_b32_e32 v218, 16, v132
	v_and_b32_e32 v219, 0xffff0000, v132
	v_lshlrev_b32_e32 v220, 16, v133
	v_and_b32_e32 v221, 0xffff0000, v133
	v_lshlrev_b32_e32 v222, 16, v134
	v_and_b32_e32 v223, 0xffff0000, v134
	v_lshlrev_b32_e32 v224, 16, v135
	v_and_b32_e32 v225, 0xffff0000, v135
	v_lshlrev_b32_e32 v226, 16, v136
	v_and_b32_e32 v227, 0xffff0000, v136
	v_lshlrev_b32_e32 v228, 16, v137
	v_and_b32_e32 v229, 0xffff0000, v137
	v_lshlrev_b32_e32 v230, 16, v138
	v_and_b32_e32 v231, 0xffff0000, v138
	v_lshlrev_b32_e32 v232, 16, v139
	v_and_b32_e32 v233, 0xffff0000, v139
	v_add_u32_e32 v237, 0x50000, v236
	global_load_dwordx4 v[132:135], v237, s[20:21]
	global_load_dwordx4 v[136:139], v237, s[64:65]
	v_pk_add_f32 v[218:219], v[218:219], v[226:227]
	v_pk_add_f32 v[220:221], v[220:221], v[228:229]
	v_pk_add_f32 v[222:223], v[222:223], v[230:231]
	v_pk_add_f32 v[224:225], v[224:225], v[232:233]
	v_pk_add_f32 v[78:79], v[218:219], v[78:79]
	v_pk_add_f32 v[80:81], v[220:221], v[80:81]
	v_pk_add_f32 v[70:71], v[222:223], v[70:71]
	v_pk_add_f32 v[72:73], v[224:225], v[72:73]
	v_pk_mul_f32 v[234:235], v[78:79], v[78:79]
	v_pk_fma_f32 v[234:235], v[80:81], v[80:81], v[234:235]
	v_pk_fma_f32 v[234:235], v[70:71], v[70:71], v[234:235]
	v_pk_fma_f32 v[234:235], v[72:73], v[72:73], v[234:235]
	v_cvt_pk_bf16_f32 v226, v78, v79
	v_cvt_pk_bf16_f32 v227, v80, v81
	v_cvt_pk_bf16_f32 v228, v70, v71
	v_cvt_pk_bf16_f32 v229, v72, v73
	global_store_dwordx4 v238, v[226:229], s[18:19]
	v_lshlrev_b32_e32 v218, 16, v226
	v_and_b32_e32 v219, 0xffff0000, v226
	v_lshlrev_b32_e32 v220, 16, v227
	v_and_b32_e32 v221, 0xffff0000, v227
	v_lshlrev_b32_e32 v222, 16, v228
	v_and_b32_e32 v223, 0xffff0000, v228
	v_lshlrev_b32_e32 v224, 16, v229
	v_and_b32_e32 v225, 0xffff0000, v229
	v_pk_add_f32 v[218:219], v[78:79], v[218:219] neg_lo:[0,1] neg_hi:[0,1]
	v_pk_add_f32 v[220:221], v[80:81], v[220:221] neg_lo:[0,1] neg_hi:[0,1]
	v_pk_add_f32 v[222:223], v[70:71], v[222:223] neg_lo:[0,1] neg_hi:[0,1]
	v_pk_add_f32 v[224:225], v[72:73], v[224:225] neg_lo:[0,1] neg_hi:[0,1]
	v_cvt_pk_bf16_f32 v230, v218, v219
	v_cvt_pk_bf16_f32 v231, v220, v221
	v_cvt_pk_bf16_f32 v232, v222, v223
	v_cvt_pk_bf16_f32 v233, v224, v225
	global_store_dwordx4 v238, v[230:233], s[64:65]
	v_pk_mul_f32 v[74:75], v[74:75], s[10:11]
	v_pk_mul_f32 v[76:77], v[76:77], s[90:91]
	v_pk_mul_f32 v[66:67], v[66:67], s[10:11]
	v_pk_mul_f32 v[68:69], v[68:69], s[90:91]
	s_waitcnt vmcnt(22)
	v_lshlrev_b32_e32 v218, 16, v140
	v_and_b32_e32 v219, 0xffff0000, v140
	v_lshlrev_b32_e32 v220, 16, v141
	v_and_b32_e32 v221, 0xffff0000, v141
	v_lshlrev_b32_e32 v222, 16, v142
	v_and_b32_e32 v223, 0xffff0000, v142
	v_lshlrev_b32_e32 v224, 16, v143
	v_and_b32_e32 v225, 0xffff0000, v143
	v_lshlrev_b32_e32 v226, 16, v144
	v_and_b32_e32 v227, 0xffff0000, v144
	v_lshlrev_b32_e32 v228, 16, v145
	v_and_b32_e32 v229, 0xffff0000, v145
	v_lshlrev_b32_e32 v230, 16, v146
	v_and_b32_e32 v231, 0xffff0000, v146
	v_lshlrev_b32_e32 v232, 16, v147
	v_and_b32_e32 v233, 0xffff0000, v147
	global_load_dwordx4 v[140:143], v237, s[20:21] offset:256
	global_load_dwordx4 v[144:147], v237, s[64:65] offset:256
	v_pk_add_f32 v[218:219], v[218:219], v[226:227]
	v_pk_add_f32 v[220:221], v[220:221], v[228:229]
	v_pk_add_f32 v[222:223], v[222:223], v[230:231]
	v_pk_add_f32 v[224:225], v[224:225], v[232:233]
	v_pk_add_f32 v[74:75], v[218:219], v[74:75]
	v_pk_add_f32 v[76:77], v[220:221], v[76:77]
	v_pk_add_f32 v[66:67], v[222:223], v[66:67]
	v_pk_add_f32 v[68:69], v[224:225], v[68:69]
	v_pk_fma_f32 v[234:235], v[74:75], v[74:75], v[234:235]
	v_pk_fma_f32 v[234:235], v[76:77], v[76:77], v[234:235]
	v_pk_fma_f32 v[234:235], v[66:67], v[66:67], v[234:235]
	v_pk_fma_f32 v[234:235], v[68:69], v[68:69], v[234:235]
	v_cvt_pk_bf16_f32 v226, v74, v75
	v_cvt_pk_bf16_f32 v227, v76, v77
	v_cvt_pk_bf16_f32 v228, v66, v67
	v_cvt_pk_bf16_f32 v229, v68, v69
	global_store_dwordx4 v238, v[226:229], s[18:19] offset:256
	v_lshlrev_b32_e32 v218, 16, v226
	v_and_b32_e32 v219, 0xffff0000, v226
	v_lshlrev_b32_e32 v220, 16, v227
	v_and_b32_e32 v221, 0xffff0000, v227
	v_lshlrev_b32_e32 v222, 16, v228
	v_and_b32_e32 v223, 0xffff0000, v228
	v_lshlrev_b32_e32 v224, 16, v229
	v_and_b32_e32 v225, 0xffff0000, v229
	v_pk_add_f32 v[218:219], v[74:75], v[218:219] neg_lo:[0,1] neg_hi:[0,1]
	v_pk_add_f32 v[220:221], v[76:77], v[220:221] neg_lo:[0,1] neg_hi:[0,1]
	v_pk_add_f32 v[222:223], v[66:67], v[222:223] neg_lo:[0,1] neg_hi:[0,1]
	v_pk_add_f32 v[224:225], v[68:69], v[224:225] neg_lo:[0,1] neg_hi:[0,1]
	v_cvt_pk_bf16_f32 v230, v218, v219
	v_cvt_pk_bf16_f32 v231, v220, v221
	v_cvt_pk_bf16_f32 v232, v222, v223
	v_cvt_pk_bf16_f32 v233, v224, v225
	global_store_dwordx4 v238, v[230:233], s[64:65] offset:256
	v_add_f32_e32 v78, v234, v235
	v_pk_mul_f32 v[62:63], v[62:63], s[10:11]
	v_pk_mul_f32 v[64:65], v[64:65], s[90:91]
	v_pk_mul_f32 v[54:55], v[54:55], s[10:11]
	v_pk_mul_f32 v[56:57], v[56:57], s[90:91]
	v_add_u32_e32 v238, 0x40000, v236
	s_waitcnt vmcnt(22)
; #define GAS __attribute__((address_space(1)))
; __device__ __forceinline__ u32x4 pack8(f32x4 a, f32x4 b) { u32x4 w; w.x = cvtpk(a[0], a[1]); w.y = cvtpk(a[2], a[3]); w.z = cvtpk(b[0], b[1]); w.w = cvtpk(b[2], b[3]); return w; }
; __device__ __forceinline__ f32x4 sig4(f32x4 x) { f32x4 r; r[0] = fsigmoid(x[0]); r[1] = fsigmoid(x[1]); r[2] = fsigmoid(x[2]); r[3] = fsigmoid(x[3]); return r; }
; __device__ __forceinline__ float dot4(f32x4 a) { return (a[0] * a[0] + a[1] * a[1]) + (a[2] * a[2] + a[3] * a[3]); }
;     __device__ __forceinline__ void operator()(const f32x4 (&acc)[2][2][4][2], const Unit& u, int wr, int wc, int fr, int fq) const {
;     ...
;                     const int row = rowb + ai * HALF + m * 16;
;                     float rstd = 1.f; if (mode == EM_PLE) rstd = __builtin_amdgcn_rsqf(ssq_in[row] * (1.0f / DM) + EPS);
;                     float ss = 0.f;
; #pragma unroll
;                     for (int bj = 0; bj < 2; ++bj) {
;                         const size_t off = (size_t)row * DM + u.pn * BM + bj * HALF + wc * 32 + fq * 8;
;                         f32x4 h0, h1, l0, l1; unpack8(*(const GAS u32x4*)(hin + off), h0, h1); unpack8(*(const GAS u32x4*)(lo + off), l0, l1);
;                         h0 += l0; h1 += l1;
;                         if (mode == EM_PLE) { f32x4 t0, t1; unpack8(*(const GAS u32x4*)(g16 + off), t0, t1);
;                             h0 += sig4(acc[ai][bj][m][0] * rstd) * t0; h1 += sig4(acc[ai][bj][m][1] * rstd) * t1; }
;                         else { h0 += acc[ai][bj][m][0] * scale; h1 += acc[ai][bj][m][1] * scale; }
;                         if (fin) { *(GAS f32x4*)(h + off) = h0; *(GAS f32x4*)(h + off + 4) = h1; }
;                         const u32x4 hw = pack8(h0, h1); f32x4 g0, g1; unpack8(hw, g0, g1);
;                         *(GAS u32x4*)(o16 + off) = hw;
;                         *(GAS u32x4*)(lo + off) = pack8(h0 - g0, h1 - g1);
;                         ss += dot4(h0) + dot4(h1);
	v_lshlrev_b32_e32 v218, 16, v148
	v_and_b32_e32 v219, 0xffff0000, v148
	v_lshlrev_b32_e32 v220, 16, v149
	v_and_b32_e32 v221, 0xffff0000, v149
	v_lshlrev_b32_e32 v222, 16, v150
	v_and_b32_e32 v223, 0xffff0000, v150
	v_lshlrev_b32_e32 v224, 16, v151
	v_and_b32_e32 v225, 0xffff0000, v151
	v_lshlrev_b32_e32 v226, 16, v152
	v_and_b32_e32 v227, 0xffff0000, v152
	v_lshlrev_b32_e32 v228, 16, v153
	v_and_b32_e32 v229, 0xffff0000, v153
	v_lshlrev_b32_e32 v230, 16, v154
	v_and_b32_e32 v231, 0xffff0000, v154
	v_lshlrev_b32_e32 v232, 16, v155
	v_and_b32_e32 v233, 0xffff0000, v155
	v_add_u32_e32 v237, 0x58000, v236
	global_load_dwordx4 v[148:151], v237, s[20:21]
	global_load_dwordx4 v[152:155], v237, s[64:65]
	v_pk_add_f32 v[218:219], v[218:219], v[226:227]
	v_pk_add_f32 v[220:221], v[220:221], v[228:229]
	v_pk_add_f32 v[222:223], v[222:223], v[230:231]
	v_pk_add_f32 v[224:225], v[224:225], v[232:233]
	v_pk_add_f32 v[62:63], v[218:219], v[62:63]
	v_pk_add_f32 v[64:65], v[220:221], v[64:65]
	v_pk_add_f32 v[54:55], v[222:223], v[54:55]
	v_pk_add_f32 v[56:57], v[224:225], v[56:57]
	v_pk_mul_f32 v[234:235], v[62:63], v[62:63]
	v_pk_fma_f32 v[234:235], v[64:65], v[64:65], v[234:235]
	v_pk_fma_f32 v[234:235], v[54:55], v[54:55], v[234:235]
	v_pk_fma_f32 v[234:235], v[56:57], v[56:57], v[234:235]
	v_cvt_pk_bf16_f32 v226, v62, v63
	v_cvt_pk_bf16_f32 v227, v64, v65
	v_cvt_pk_bf16_f32 v228, v54, v55
	v_cvt_pk_bf16_f32 v229, v56, v57
	global_store_dwordx4 v238, v[226:229], s[18:19]
	v_lshlrev_b32_e32 v218, 16, v226
	v_and_b32_e32 v219, 0xffff0000, v226
	v_lshlrev_b32_e32 v220, 16, v227
	v_and_b32_e32 v221, 0xffff0000, v227
	v_lshlrev_b32_e32 v222, 16, v228
	v_and_b32_e32 v223, 0xffff0000, v228
	v_lshlrev_b32_e32 v224, 16, v229
	v_and_b32_e32 v225, 0xffff0000, v229
	v_pk_add_f32 v[218:219], v[62:63], v[218:219] neg_lo:[0,1] neg_hi:[0,1]
	v_pk_add_f32 v[220:221], v[64:65], v[220:221] neg_lo:[0,1] neg_hi:[0,1]
	v_pk_add_f32 v[222:223], v[54:55], v[222:223] neg_lo:[0,1] neg_hi:[0,1]
	v_pk_add_f32 v[224:225], v[56:57], v[224:225] neg_lo:[0,1] neg_hi:[0,1]
	v_cvt_pk_bf16_f32 v230, v218, v219
	v_cvt_pk_bf16_f32 v231, v220, v221
	v_cvt_pk_bf16_f32 v232, v222, v223
	v_cvt_pk_bf16_f32 v233, v224, v225
	global_store_dwordx4 v238, v[230:233], s[64:65]
	v_pk_mul_f32 v[58:59], v[58:59], s[10:11]
	v_pk_mul_f32 v[60:61], v[60:61], s[90:91]
	v_pk_mul_f32 v[50:51], v[50:51], s[10:11]
	v_pk_mul_f32 v[52:53], v[52:53], s[90:91]
	s_waitcnt vmcnt(22)
	v_lshlrev_b32_e32 v218, 16, v184
	v_and_b32_e32 v219, 0xffff0000, v184
	v_lshlrev_b32_e32 v220, 16, v185
	v_and_b32_e32 v221, 0xffff0000, v185
	v_lshlrev_b32_e32 v222, 16, v186
	v_and_b32_e32 v223, 0xffff0000, v186
	v_lshlrev_b32_e32 v224, 16, v187
	v_and_b32_e32 v225, 0xffff0000, v187
	v_lshlrev_b32_e32 v226, 16, v188
	v_and_b32_e32 v227, 0xffff0000, v188
	v_lshlrev_b32_e32 v228, 16, v189
	v_and_b32_e32 v229, 0xffff0000, v189
	v_lshlrev_b32_e32 v230, 16, v190
	v_and_b32_e32 v231, 0xffff0000, v190
	v_lshlrev_b32_e32 v232, 16, v191
	v_and_b32_e32 v233, 0xffff0000, v191
	global_load_dwordx4 v[184:187], v237, s[20:21] offset:256
	global_load_dwordx4 v[188:191], v237, s[64:65] offset:256
	v_pk_add_f32 v[218:219], v[218:219], v[226:227]
	v_pk_add_f32 v[220:221], v[220:221], v[228:229]
	v_pk_add_f32 v[222:223], v[222:223], v[230:231]
	v_pk_add_f32 v[224:225], v[224:225], v[232:233]
	v_pk_add_f32 v[58:59], v[218:219], v[58:59]
	v_pk_add_f32 v[60:61], v[220:221], v[60:61]
	v_pk_add_f32 v[50:51], v[222:223], v[50:51]
	v_pk_add_f32 v[52:53], v[224:225], v[52:53]
	v_pk_fma_f32 v[234:235], v[58:59], v[58:59], v[234:235]
	v_pk_fma_f32 v[234:235], v[60:61], v[60:61], v[234:235]
	v_pk_fma_f32 v[234:235], v[50:51], v[50:51], v[234:235]
	v_pk_fma_f32 v[234:235], v[52:53], v[52:53], v[234:235]
	v_cvt_pk_bf16_f32 v226, v58, v59
	v_cvt_pk_bf16_f32 v227, v60, v61
	v_cvt_pk_bf16_f32 v228, v50, v51
	v_cvt_pk_bf16_f32 v229, v52, v53
	global_store_dwordx4 v238, v[226:229], s[18:19] offset:256
	v_lshlrev_b32_e32 v218, 16, v226
	v_and_b32_e32 v219, 0xffff0000, v226
	v_lshlrev_b32_e32 v220, 16, v227
	v_and_b32_e32 v221, 0xffff0000, v227
	v_lshlrev_b32_e32 v222, 16, v228
	v_and_b32_e32 v223, 0xffff0000, v228
	v_lshlrev_b32_e32 v224, 16, v229
	v_and_b32_e32 v225, 0xffff0000, v229
	v_pk_add_f32 v[218:219], v[58:59], v[218:219] neg_lo:[0,1] neg_hi:[0,1]
	v_pk_add_f32 v[220:221], v[60:61], v[220:221] neg_lo:[0,1] neg_hi:[0,1]
	v_pk_add_f32 v[222:223], v[50:51], v[222:223] neg_lo:[0,1] neg_hi:[0,1]
	v_pk_add_f32 v[224:225], v[52:53], v[224:225] neg_lo:[0,1] neg_hi:[0,1]
	v_cvt_pk_bf16_f32 v230, v218, v219
	v_cvt_pk_bf16_f32 v231, v220, v221
	v_cvt_pk_bf16_f32 v232, v222, v223
	v_cvt_pk_bf16_f32 v233, v224, v225
	global_store_dwordx4 v238, v[230:233], s[64:65] offset:256
	v_add_f32_e32 v62, v234, v235
	v_pk_mul_f32 v[46:47], v[46:47], s[10:11]
	v_pk_mul_f32 v[48:49], v[48:49], s[90:91]
	v_pk_mul_f32 v[38:39], v[38:39], s[10:11]
	v_pk_mul_f32 v[40:41], v[40:41], s[90:91]
	v_add_u32_e32 v238, 0x48000, v236
	s_waitcnt vmcnt(22)
; #define GAS __attribute__((address_space(1)))
; __device__ __forceinline__ u32x4 pack8(f32x4 a, f32x4 b) { u32x4 w; w.x = cvtpk(a[0], a[1]); w.y = cvtpk(a[2], a[3]); w.z = cvtpk(b[0], b[1]); w.w = cvtpk(b[2], b[3]); return w; }
; __device__ __forceinline__ f32x4 sig4(f32x4 x) { f32x4 r; r[0] = fsigmoid(x[0]); r[1] = fsigmoid(x[1]); r[2] = fsigmoid(x[2]); r[3] = fsigmoid(x[3]); return r; }
; __device__ __forceinline__ float dot4(f32x4 a) { return (a[0] * a[0] + a[1] * a[1]) + (a[2] * a[2] + a[3] * a[3]); }
;     __device__ __forceinline__ void operator()(const f32x4 (&acc)[2][2][4][2], const Unit& u, int wr, int wc, int fr, int fq) const {
;     ...
;                     const int row = rowb + ai * HALF + m * 16;
;                     float rstd = 1.f; if (mode == EM_PLE) rstd = __builtin_amdgcn_rsqf(ssq_in[row] * (1.0f / DM) + EPS);
;                     float ss = 0.f;
; #pragma unroll
;                     for (int bj = 0; bj < 2; ++bj) {
;                         const size_t off = (size_t)row * DM + u.pn * BM + bj * HALF + wc * 32 + fq * 8;
;                         f32x4 h0, h1, l0, l1; unpack8(*(const GAS u32x4*)(hin + off), h0, h1); unpack8(*(const GAS u32x4*)(lo + off), l0, l1);
;                         h0 += l0; h1 += l1;
;                         if (mode == EM_PLE) { f32x4 t0, t1; unpack8(*(const GAS u32x4*)(g16 + off), t0, t1);
;                             h0 += sig4(acc[ai][bj][m][0] * rstd) * t0; h1 += sig4(acc[ai][bj][m][1] * rstd) * t1; }
;                         else { h0 += acc[ai][bj][m][0] * scale; h1 += acc[ai][bj][m][1] * scale; }
;                         if (fin) { *(GAS f32x4*)(h + off) = h0; *(GAS f32x4*)(h + off + 4) = h1; }
;                         const u32x4 hw = pack8(h0, h1); f32x4 g0, g1; unpack8(hw, g0, g1);
;                         *(GAS u32x4*)(o16 + off) = hw;
;                         *(GAS u32x4*)(lo + off) = pack8(h0 - g0, h1 - g1);
;                         ss += dot4(h0) + dot4(h1);
	v_lshlrev_b32_e32 v218, 16, v192
	v_and_b32_e32 v219, 0xffff0000, v192
	v_lshlrev_b32_e32 v220, 16, v193
	v_and_b32_e32 v221, 0xffff0000, v193
	v_lshlrev_b32_e32 v222, 16, v194
	v_and_b32_e32 v223, 0xffff0000, v194
	v_lshlrev_b32_e32 v224, 16, v195
	v_and_b32_e32 v225, 0xffff0000, v195
	v_lshlrev_b32_e32 v226, 16, v196
	v_and_b32_e32 v227, 0xffff0000, v196
	v_lshlrev_b32_e32 v228, 16, v197
	v_and_b32_e32 v229, 0xffff0000, v197
	v_lshlrev_b32_e32 v230, 16, v198
	v_and_b32_e32 v231, 0xffff0000, v198
	v_lshlrev_b32_e32 v232, 16, v199
	v_and_b32_e32 v233, 0xffff0000, v199
	v_pk_add_f32 v[218:219], v[218:219], v[226:227]
	v_pk_add_f32 v[220:221], v[220:221], v[228:229]
	v_pk_add_f32 v[222:223], v[222:223], v[230:231]
	v_pk_add_f32 v[224:225], v[224:225], v[232:233]
	v_pk_add_f32 v[46:47], v[218:219], v[46:47]
	v_pk_add_f32 v[48:49], v[220:221], v[48:49]
	v_pk_add_f32 v[38:39], v[222:223], v[38:39]
	v_pk_add_f32 v[40:41], v[224:225], v[40:41]
	v_pk_mul_f32 v[234:235], v[46:47], v[46:47]
	v_pk_fma_f32 v[234:235], v[48:49], v[48:49], v[234:235]
	v_pk_fma_f32 v[234:235], v[38:39], v[38:39], v[234:235]
	v_pk_fma_f32 v[234:235], v[40:41], v[40:41], v[234:235]
	v_cvt_pk_bf16_f32 v226, v46, v47
	v_cvt_pk_bf16_f32 v227, v48, v49
	v_cvt_pk_bf16_f32 v228, v38, v39
	v_cvt_pk_bf16_f32 v229, v40, v41
	global_store_dwordx4 v238, v[226:229], s[18:19]
	v_lshlrev_b32_e32 v218, 16, v226
	v_and_b32_e32 v219, 0xffff0000, v226
	v_lshlrev_b32_e32 v220, 16, v227
	v_and_b32_e32 v221, 0xffff0000, v227
	v_lshlrev_b32_e32 v222, 16, v228
	v_and_b32_e32 v223, 0xffff0000, v228
	v_lshlrev_b32_e32 v224, 16, v229
	v_and_b32_e32 v225, 0xffff0000, v229
	v_pk_add_f32 v[218:219], v[46:47], v[218:219] neg_lo:[0,1] neg_hi:[0,1]
	v_pk_add_f32 v[220:221], v[48:49], v[220:221] neg_lo:[0,1] neg_hi:[0,1]
	v_pk_add_f32 v[222:223], v[38:39], v[222:223] neg_lo:[0,1] neg_hi:[0,1]
	v_pk_add_f32 v[224:225], v[40:41], v[224:225] neg_lo:[0,1] neg_hi:[0,1]
	v_cvt_pk_bf16_f32 v230, v218, v219
	v_cvt_pk_bf16_f32 v231, v220, v221
	v_cvt_pk_bf16_f32 v232, v222, v223
	v_cvt_pk_bf16_f32 v233, v224, v225
	global_store_dwordx4 v238, v[230:233], s[64:65]
	v_pk_mul_f32 v[42:43], v[42:43], s[10:11]
	v_pk_mul_f32 v[44:45], v[44:45], s[90:91]
	v_pk_mul_f32 v[34:35], v[34:35], s[10:11]
	v_pk_mul_f32 v[36:37], v[36:37], s[90:91]
	s_waitcnt vmcnt(20)
	v_lshlrev_b32_e32 v218, 16, v200
	v_and_b32_e32 v219, 0xffff0000, v200
	v_lshlrev_b32_e32 v220, 16, v201
	v_and_b32_e32 v221, 0xffff0000, v201
	v_lshlrev_b32_e32 v222, 16, v202
	v_and_b32_e32 v223, 0xffff0000, v202
	v_lshlrev_b32_e32 v224, 16, v203
	v_and_b32_e32 v225, 0xffff0000, v203
	v_lshlrev_b32_e32 v226, 16, v204
	v_and_b32_e32 v227, 0xffff0000, v204
	v_lshlrev_b32_e32 v228, 16, v205
	v_and_b32_e32 v229, 0xffff0000, v205
	v_lshlrev_b32_e32 v230, 16, v206
	v_and_b32_e32 v231, 0xffff0000, v206
	v_lshlrev_b32_e32 v232, 16, v207
	v_and_b32_e32 v233, 0xffff0000, v207
	v_pk_add_f32 v[218:219], v[218:219], v[226:227]
	v_pk_add_f32 v[220:221], v[220:221], v[228:229]
	v_pk_add_f32 v[222:223], v[222:223], v[230:231]
	v_pk_add_f32 v[224:225], v[224:225], v[232:233]
	v_pk_add_f32 v[42:43], v[218:219], v[42:43]
	v_pk_add_f32 v[44:45], v[220:221], v[44:45]
	v_pk_add_f32 v[34:35], v[222:223], v[34:35]
	v_pk_add_f32 v[36:37], v[224:225], v[36:37]
	v_pk_fma_f32 v[234:235], v[42:43], v[42:43], v[234:235]
	v_pk_fma_f32 v[234:235], v[44:45], v[44:45], v[234:235]
	v_pk_fma_f32 v[234:235], v[34:35], v[34:35], v[234:235]
	v_pk_fma_f32 v[234:235], v[36:37], v[36:37], v[234:235]
	v_cvt_pk_bf16_f32 v226, v42, v43
	v_cvt_pk_bf16_f32 v227, v44, v45
	v_cvt_pk_bf16_f32 v228, v34, v35
	v_cvt_pk_bf16_f32 v229, v36, v37
	global_store_dwordx4 v238, v[226:229], s[18:19] offset:256
	v_lshlrev_b32_e32 v218, 16, v226
	v_and_b32_e32 v219, 0xffff0000, v226
	v_lshlrev_b32_e32 v220, 16, v227
	v_and_b32_e32 v221, 0xffff0000, v227
	v_lshlrev_b32_e32 v222, 16, v228
	v_and_b32_e32 v223, 0xffff0000, v228
	v_lshlrev_b32_e32 v224, 16, v229
	v_and_b32_e32 v225, 0xffff0000, v229
	v_pk_add_f32 v[218:219], v[42:43], v[218:219] neg_lo:[0,1] neg_hi:[0,1]
	v_pk_add_f32 v[220:221], v[44:45], v[220:221] neg_lo:[0,1] neg_hi:[0,1]
	v_pk_add_f32 v[222:223], v[34:35], v[222:223] neg_lo:[0,1] neg_hi:[0,1]
	v_pk_add_f32 v[224:225], v[36:37], v[224:225] neg_lo:[0,1] neg_hi:[0,1]
	v_cvt_pk_bf16_f32 v230, v218, v219
	v_cvt_pk_bf16_f32 v231, v220, v221
	v_cvt_pk_bf16_f32 v232, v222, v223
	v_cvt_pk_bf16_f32 v233, v224, v225
	global_store_dwordx4 v238, v[230:233], s[64:65] offset:256
	v_add_f32_e32 v46, v234, v235
	v_pk_mul_f32 v[30:31], v[30:31], s[10:11]
	v_pk_mul_f32 v[32:33], v[32:33], s[90:91]
	v_pk_mul_f32 v[22:23], v[22:23], s[10:11]
	v_pk_mul_f32 v[24:25], v[24:25], s[90:91]
	v_add_u32_e32 v238, 0x50000, v236
	s_waitcnt vmcnt(18)
; #define GAS __attribute__((address_space(1)))
; __device__ __forceinline__ u32x4 pack8(f32x4 a, f32x4 b) { u32x4 w; w.x = cvtpk(a[0], a[1]); w.y = cvtpk(a[2], a[3]); w.z = cvtpk(b[0], b[1]); w.w = cvtpk(b[2], b[3]); return w; }
; __device__ __forceinline__ f32x4 sig4(f32x4 x) { f32x4 r; r[0] = fsigmoid(x[0]); r[1] = fsigmoid(x[1]); r[2] = fsigmoid(x[2]); r[3] = fsigmoid(x[3]); return r; }
; __device__ __forceinline__ float dot4(f32x4 a) { return (a[0] * a[0] + a[1] * a[1]) + (a[2] * a[2] + a[3] * a[3]); }
;     __device__ __forceinline__ void operator()(const f32x4 (&acc)[2][2][4][2], const Unit& u, int wr, int wc, int fr, int fq) const {
;     ...
;                     const int row = rowb + ai * HALF + m * 16;
;                     float rstd = 1.f; if (mode == EM_PLE) rstd = __builtin_amdgcn_rsqf(ssq_in[row] * (1.0f / DM) + EPS);
;                     float ss = 0.f;
; #pragma unroll
;                     for (int bj = 0; bj < 2; ++bj) {
;                         const size_t off = (size_t)row * DM + u.pn * BM + bj * HALF + wc * 32 + fq * 8;
;                         f32x4 h0, h1, l0, l1; unpack8(*(const GAS u32x4*)(hin + off), h0, h1); unpack8(*(const GAS u32x4*)(lo + off), l0, l1);
;                         h0 += l0; h1 += l1;
;                         if (mode == EM_PLE) { f32x4 t0, t1; unpack8(*(const GAS u32x4*)(g16 + off), t0, t1);
;                             h0 += sig4(acc[ai][bj][m][0] * rstd) * t0; h1 += sig4(acc[ai][bj][m][1] * rstd) * t1; }
;                         else { h0 += acc[ai][bj][m][0] * scale; h1 += acc[ai][bj][m][1] * scale; }
;                         if (fin) { *(GAS f32x4*)(h + off) = h0; *(GAS f32x4*)(h + off + 4) = h1; }
;                         const u32x4 hw = pack8(h0, h1); f32x4 g0, g1; unpack8(hw, g0, g1);
;                         *(GAS u32x4*)(o16 + off) = hw;
;                         *(GAS u32x4*)(lo + off) = pack8(h0 - g0, h1 - g1);
;                         ss += dot4(h0) + dot4(h1);
	v_lshlrev_b32_e32 v218, 16, v132
	v_and_b32_e32 v219, 0xffff0000, v132
	v_lshlrev_b32_e32 v220, 16, v133
	v_and_b32_e32 v221, 0xffff0000, v133
	v_lshlrev_b32_e32 v222, 16, v134
	v_and_b32_e32 v223, 0xffff0000, v134
	v_lshlrev_b32_e32 v224, 16, v135
	v_and_b32_e32 v225, 0xffff0000, v135
	v_lshlrev_b32_e32 v226, 16, v136
	v_and_b32_e32 v227, 0xffff0000, v136
	v_lshlrev_b32_e32 v228, 16, v137
	v_and_b32_e32 v229, 0xffff0000, v137
	v_lshlrev_b32_e32 v230, 16, v138
	v_and_b32_e32 v231, 0xffff0000, v138
	v_lshlrev_b32_e32 v232, 16, v139
	v_and_b32_e32 v233, 0xffff0000, v139
	v_pk_add_f32 v[218:219], v[218:219], v[226:227]
	v_pk_add_f32 v[220:221], v[220:221], v[228:229]
	v_pk_add_f32 v[222:223], v[222:223], v[230:231]
	v_pk_add_f32 v[224:225], v[224:225], v[232:233]
	v_pk_add_f32 v[30:31], v[218:219], v[30:31]
	v_pk_add_f32 v[32:33], v[220:221], v[32:33]
	v_pk_add_f32 v[22:23], v[222:223], v[22:23]
	v_pk_add_f32 v[24:25], v[224:225], v[24:25]
	v_pk_mul_f32 v[234:235], v[30:31], v[30:31]
	v_pk_fma_f32 v[234:235], v[32:33], v[32:33], v[234:235]
	v_pk_fma_f32 v[234:235], v[22:23], v[22:23], v[234:235]
	v_pk_fma_f32 v[234:235], v[24:25], v[24:25], v[234:235]
	v_cvt_pk_bf16_f32 v226, v30, v31
	v_cvt_pk_bf16_f32 v227, v32, v33
	v_cvt_pk_bf16_f32 v228, v22, v23
	v_cvt_pk_bf16_f32 v229, v24, v25
	global_store_dwordx4 v238, v[226:229], s[18:19]
	v_lshlrev_b32_e32 v218, 16, v226
	v_and_b32_e32 v219, 0xffff0000, v226
	v_lshlrev_b32_e32 v220, 16, v227
	v_and_b32_e32 v221, 0xffff0000, v227
	v_lshlrev_b32_e32 v222, 16, v228
	v_and_b32_e32 v223, 0xffff0000, v228
	v_lshlrev_b32_e32 v224, 16, v229
	v_and_b32_e32 v225, 0xffff0000, v229
	v_pk_add_f32 v[218:219], v[30:31], v[218:219] neg_lo:[0,1] neg_hi:[0,1]
	v_pk_add_f32 v[220:221], v[32:33], v[220:221] neg_lo:[0,1] neg_hi:[0,1]
	v_pk_add_f32 v[222:223], v[22:23], v[222:223] neg_lo:[0,1] neg_hi:[0,1]
	v_pk_add_f32 v[224:225], v[24:25], v[224:225] neg_lo:[0,1] neg_hi:[0,1]
	v_cvt_pk_bf16_f32 v230, v218, v219
	v_cvt_pk_bf16_f32 v231, v220, v221
	v_cvt_pk_bf16_f32 v232, v222, v223
	v_cvt_pk_bf16_f32 v233, v224, v225
	global_store_dwordx4 v238, v[230:233], s[64:65]
	v_pk_mul_f32 v[26:27], v[26:27], s[10:11]
	v_pk_mul_f32 v[28:29], v[28:29], s[90:91]
	v_pk_mul_f32 v[18:19], v[18:19], s[10:11]
	v_pk_mul_f32 v[20:21], v[20:21], s[90:91]
	s_waitcnt vmcnt(16)
	v_lshlrev_b32_e32 v218, 16, v140
	v_and_b32_e32 v219, 0xffff0000, v140
	v_lshlrev_b32_e32 v220, 16, v141
	v_and_b32_e32 v221, 0xffff0000, v141
	v_lshlrev_b32_e32 v222, 16, v142
	v_and_b32_e32 v223, 0xffff0000, v142
	v_lshlrev_b32_e32 v224, 16, v143
	v_and_b32_e32 v225, 0xffff0000, v143
	v_lshlrev_b32_e32 v226, 16, v144
	v_and_b32_e32 v227, 0xffff0000, v144
	v_lshlrev_b32_e32 v228, 16, v145
	v_and_b32_e32 v229, 0xffff0000, v145
	v_lshlrev_b32_e32 v230, 16, v146
	v_and_b32_e32 v231, 0xffff0000, v146
	v_lshlrev_b32_e32 v232, 16, v147
	v_and_b32_e32 v233, 0xffff0000, v147
	v_pk_add_f32 v[218:219], v[218:219], v[226:227]
	v_pk_add_f32 v[220:221], v[220:221], v[228:229]
	v_pk_add_f32 v[222:223], v[222:223], v[230:231]
	v_pk_add_f32 v[224:225], v[224:225], v[232:233]
	v_pk_add_f32 v[26:27], v[218:219], v[26:27]
	v_pk_add_f32 v[28:29], v[220:221], v[28:29]
	v_pk_add_f32 v[18:19], v[222:223], v[18:19]
	v_pk_add_f32 v[20:21], v[224:225], v[20:21]
	v_pk_fma_f32 v[234:235], v[26:27], v[26:27], v[234:235]
	v_pk_fma_f32 v[234:235], v[28:29], v[28:29], v[234:235]
	v_pk_fma_f32 v[234:235], v[18:19], v[18:19], v[234:235]
	v_pk_fma_f32 v[234:235], v[20:21], v[20:21], v[234:235]
	v_cvt_pk_bf16_f32 v226, v26, v27
	v_cvt_pk_bf16_f32 v227, v28, v29
	v_cvt_pk_bf16_f32 v228, v18, v19
	v_cvt_pk_bf16_f32 v229, v20, v21
	global_store_dwordx4 v238, v[226:229], s[18:19] offset:256
	v_lshlrev_b32_e32 v218, 16, v226
	v_and_b32_e32 v219, 0xffff0000, v226
	v_lshlrev_b32_e32 v220, 16, v227
	v_and_b32_e32 v221, 0xffff0000, v227
	v_lshlrev_b32_e32 v222, 16, v228
	v_and_b32_e32 v223, 0xffff0000, v228
	v_lshlrev_b32_e32 v224, 16, v229
	v_and_b32_e32 v225, 0xffff0000, v229
	v_pk_add_f32 v[218:219], v[26:27], v[218:219] neg_lo:[0,1] neg_hi:[0,1]
	v_pk_add_f32 v[220:221], v[28:29], v[220:221] neg_lo:[0,1] neg_hi:[0,1]
	v_pk_add_f32 v[222:223], v[18:19], v[222:223] neg_lo:[0,1] neg_hi:[0,1]
	v_pk_add_f32 v[224:225], v[20:21], v[224:225] neg_lo:[0,1] neg_hi:[0,1]
	v_cvt_pk_bf16_f32 v230, v218, v219
	v_cvt_pk_bf16_f32 v231, v220, v221
	v_cvt_pk_bf16_f32 v232, v222, v223
	v_cvt_pk_bf16_f32 v233, v224, v225
	global_store_dwordx4 v238, v[230:233], s[64:65] offset:256
	v_add_f32_e32 v30, v234, v235
	v_pk_mul_f32 v[14:15], v[14:15], s[10:11]
	v_pk_mul_f32 v[16:17], v[16:17], s[90:91]
	v_pk_mul_f32 v[6:7], v[6:7], s[10:11]
	v_pk_mul_f32 v[8:9], v[8:9], s[90:91]
	v_add_u32_e32 v238, 0x58000, v236
	s_waitcnt vmcnt(14)
; #define GAS __attribute__((address_space(1)))
; __device__ __forceinline__ u32x4 pack8(f32x4 a, f32x4 b) { u32x4 w; w.x = cvtpk(a[0], a[1]); w.y = cvtpk(a[2], a[3]); w.z = cvtpk(b[0], b[1]); w.w = cvtpk(b[2], b[3]); return w; }
; __device__ __forceinline__ f32x4 sig4(f32x4 x) { f32x4 r; r[0] = fsigmoid(x[0]); r[1] = fsigmoid(x[1]); r[2] = fsigmoid(x[2]); r[3] = fsigmoid(x[3]); return r; }
; __device__ __forceinline__ float dot4(f32x4 a) { return (a[0] * a[0] + a[1] * a[1]) + (a[2] * a[2] + a[3] * a[3]); }
;     __device__ __forceinline__ void operator()(const f32x4 (&acc)[2][2][4][2], const Unit& u, int wr, int wc, int fr, int fq) const {
;     ...
;                     const int row = rowb + ai * HALF + m * 16;
;                     float rstd = 1.f; if (mode == EM_PLE) rstd = __builtin_amdgcn_rsqf(ssq_in[row] * (1.0f / DM) + EPS);
;                     float ss = 0.f;
; #pragma unroll
;                     for (int bj = 0; bj < 2; ++bj) {
;                         const size_t off = (size_t)row * DM + u.pn * BM + bj * HALF + wc * 32 + fq * 8;
;                         f32x4 h0, h1, l0, l1; unpack8(*(const GAS u32x4*)(hin + off), h0, h1); unpack8(*(const GAS u32x4*)(lo + off), l0, l1);
;                         h0 += l0; h1 += l1;
;                         if (mode == EM_PLE) { f32x4 t0, t1; unpack8(*(const GAS u32x4*)(g16 + off), t0, t1);
;                             h0 += sig4(acc[ai][bj][m][0] * rstd) * t0; h1 += sig4(acc[ai][bj][m][1] * rstd) * t1; }
;                         else { h0 += acc[ai][bj][m][0] * scale; h1 += acc[ai][bj][m][1] * scale; }
;                         if (fin) { *(GAS f32x4*)(h + off) = h0; *(GAS f32x4*)(h + off + 4) = h1; }
;                         const u32x4 hw = pack8(h0, h1); f32x4 g0, g1; unpack8(hw, g0, g1);
;                         *(GAS u32x4*)(o16 + off) = hw;
;                         *(GAS u32x4*)(lo + off) = pack8(h0 - g0, h1 - g1);
;                         ss += dot4(h0) + dot4(h1);
;                     }
;                     ss += __shfl_xor(ss, 16); ss += __shfl_xor(ss, 32);
;                     if (fq == 0) (void)__hip_atomic_fetch_add(ssq_out + row, ss, __ATOMIC_RELAXED, __HIP_MEMORY_SCOPE_AGENT);
	v_lshlrev_b32_e32 v218, 16, v148
	v_and_b32_e32 v219, 0xffff0000, v148
	v_lshlrev_b32_e32 v220, 16, v149
	v_and_b32_e32 v221, 0xffff0000, v149
	v_lshlrev_b32_e32 v222, 16, v150
	v_and_b32_e32 v223, 0xffff0000, v150
	v_lshlrev_b32_e32 v224, 16, v151
	v_and_b32_e32 v225, 0xffff0000, v151
	v_lshlrev_b32_e32 v226, 16, v152
	v_and_b32_e32 v227, 0xffff0000, v152
	v_lshlrev_b32_e32 v228, 16, v153
	v_and_b32_e32 v229, 0xffff0000, v153
	v_lshlrev_b32_e32 v230, 16, v154
	v_and_b32_e32 v231, 0xffff0000, v154
	v_lshlrev_b32_e32 v232, 16, v155
	v_and_b32_e32 v233, 0xffff0000, v155
	v_pk_add_f32 v[218:219], v[218:219], v[226:227]
	v_pk_add_f32 v[220:221], v[220:221], v[228:229]
	v_pk_add_f32 v[222:223], v[222:223], v[230:231]
	v_pk_add_f32 v[224:225], v[224:225], v[232:233]
	v_pk_add_f32 v[14:15], v[218:219], v[14:15]
	v_pk_add_f32 v[16:17], v[220:221], v[16:17]
	v_pk_add_f32 v[6:7], v[222:223], v[6:7]
	v_pk_add_f32 v[8:9], v[224:225], v[8:9]
	v_pk_mul_f32 v[234:235], v[14:15], v[14:15]
	v_pk_fma_f32 v[234:235], v[16:17], v[16:17], v[234:235]
	v_pk_fma_f32 v[234:235], v[6:7], v[6:7], v[234:235]
	v_pk_fma_f32 v[234:235], v[8:9], v[8:9], v[234:235]
	v_cvt_pk_bf16_f32 v226, v14, v15
	v_cvt_pk_bf16_f32 v227, v16, v17
	v_cvt_pk_bf16_f32 v228, v6, v7
	v_cvt_pk_bf16_f32 v229, v8, v9
	global_store_dwordx4 v238, v[226:229], s[18:19]
	v_lshlrev_b32_e32 v218, 16, v226
	v_and_b32_e32 v219, 0xffff0000, v226
	v_lshlrev_b32_e32 v220, 16, v227
	v_and_b32_e32 v221, 0xffff0000, v227
	v_lshlrev_b32_e32 v222, 16, v228
	v_and_b32_e32 v223, 0xffff0000, v228
	v_lshlrev_b32_e32 v224, 16, v229
	v_and_b32_e32 v225, 0xffff0000, v229
	v_pk_add_f32 v[218:219], v[14:15], v[218:219] neg_lo:[0,1] neg_hi:[0,1]
	v_pk_add_f32 v[220:221], v[16:17], v[220:221] neg_lo:[0,1] neg_hi:[0,1]
	v_pk_add_f32 v[222:223], v[6:7], v[222:223] neg_lo:[0,1] neg_hi:[0,1]
	v_pk_add_f32 v[224:225], v[8:9], v[224:225] neg_lo:[0,1] neg_hi:[0,1]
	v_cvt_pk_bf16_f32 v230, v218, v219
	v_cvt_pk_bf16_f32 v231, v220, v221
	v_cvt_pk_bf16_f32 v232, v222, v223
	v_cvt_pk_bf16_f32 v233, v224, v225
	global_store_dwordx4 v238, v[230:233], s[64:65]
	v_pk_mul_f32 v[10:11], v[10:11], s[10:11]
	v_pk_mul_f32 v[12:13], v[12:13], s[90:91]
	v_pk_mul_f32 v[2:3], v[2:3], s[10:11]
	v_pk_mul_f32 v[4:5], v[4:5], s[90:91]
	s_waitcnt vmcnt(12)
	v_lshlrev_b32_e32 v218, 16, v184
	v_and_b32_e32 v219, 0xffff0000, v184
	v_lshlrev_b32_e32 v220, 16, v185
	v_and_b32_e32 v221, 0xffff0000, v185
	v_lshlrev_b32_e32 v222, 16, v186
	v_and_b32_e32 v223, 0xffff0000, v186
	v_lshlrev_b32_e32 v224, 16, v187
	v_and_b32_e32 v225, 0xffff0000, v187
	v_lshlrev_b32_e32 v226, 16, v188
	v_and_b32_e32 v227, 0xffff0000, v188
	v_lshlrev_b32_e32 v228, 16, v189
	v_and_b32_e32 v229, 0xffff0000, v189
	v_lshlrev_b32_e32 v230, 16, v190
	v_and_b32_e32 v231, 0xffff0000, v190
	v_lshlrev_b32_e32 v232, 16, v191
	v_and_b32_e32 v233, 0xffff0000, v191
	v_pk_add_f32 v[218:219], v[218:219], v[226:227]
	v_pk_add_f32 v[220:221], v[220:221], v[228:229]
	v_pk_add_f32 v[222:223], v[222:223], v[230:231]
	v_pk_add_f32 v[224:225], v[224:225], v[232:233]
	v_pk_add_f32 v[10:11], v[218:219], v[10:11]
	v_pk_add_f32 v[12:13], v[220:221], v[12:13]
	v_pk_add_f32 v[2:3], v[222:223], v[2:3]
	v_pk_add_f32 v[4:5], v[224:225], v[4:5]
	v_pk_fma_f32 v[234:235], v[10:11], v[10:11], v[234:235]
	v_pk_fma_f32 v[234:235], v[12:13], v[12:13], v[234:235]
	v_pk_fma_f32 v[234:235], v[2:3], v[2:3], v[234:235]
	v_pk_fma_f32 v[234:235], v[4:5], v[4:5], v[234:235]
	v_cvt_pk_bf16_f32 v226, v10, v11
	v_cvt_pk_bf16_f32 v227, v12, v13
	v_cvt_pk_bf16_f32 v228, v2, v3
	v_cvt_pk_bf16_f32 v229, v4, v5
	global_store_dwordx4 v238, v[226:229], s[18:19] offset:256
	v_lshlrev_b32_e32 v218, 16, v226
	v_and_b32_e32 v219, 0xffff0000, v226
	v_lshlrev_b32_e32 v220, 16, v227
	v_and_b32_e32 v221, 0xffff0000, v227
	v_lshlrev_b32_e32 v222, 16, v228
	v_and_b32_e32 v223, 0xffff0000, v228
	v_lshlrev_b32_e32 v224, 16, v229
	v_and_b32_e32 v225, 0xffff0000, v229
	v_pk_add_f32 v[218:219], v[10:11], v[218:219] neg_lo:[0,1] neg_hi:[0,1]
	v_pk_add_f32 v[220:221], v[12:13], v[220:221] neg_lo:[0,1] neg_hi:[0,1]
	v_pk_add_f32 v[222:223], v[2:3], v[222:223] neg_lo:[0,1] neg_hi:[0,1]
	v_pk_add_f32 v[224:225], v[4:5], v[224:225] neg_lo:[0,1] neg_hi:[0,1]
	v_cvt_pk_bf16_f32 v230, v218, v219
	v_cvt_pk_bf16_f32 v231, v220, v221
	v_cvt_pk_bf16_f32 v232, v222, v223
	v_cvt_pk_bf16_f32 v233, v224, v225
	global_store_dwordx4 v238, v[230:233], s[64:65] offset:256
	v_add_f32_e32 v14, v234, v235
	v_xor_b32_e32 v130, 16, v214
	v_xor_b32_e32 v131, 32, v214
	v_lshlrev_b32_e32 v130, 2, v130
	v_lshlrev_b32_e32 v131, 2, v131
	ds_bpermute_b32 v218, v130, v114
	ds_bpermute_b32 v219, v130, v110
	ds_bpermute_b32 v220, v130, v94
	ds_bpermute_b32 v221, v130, v78
	ds_bpermute_b32 v222, v130, v62
	ds_bpermute_b32 v223, v130, v46
	ds_bpermute_b32 v224, v130, v30
	ds_bpermute_b32 v225, v130, v14
	s_waitcnt lgkmcnt(0)
	v_add_f32_e32 v114, v114, v218
	v_add_f32_e32 v110, v110, v219
	v_add_f32_e32 v94, v94, v220
	v_add_f32_e32 v78, v78, v221
	v_add_f32_e32 v62, v62, v222
	v_add_f32_e32 v46, v46, v223
	v_add_f32_e32 v30, v30, v224
	v_add_f32_e32 v14, v14, v225
	ds_bpermute_b32 v218, v131, v114
	ds_bpermute_b32 v219, v131, v110
	ds_bpermute_b32 v220, v131, v94
	ds_bpermute_b32 v221, v131, v78
	ds_bpermute_b32 v222, v131, v62
	ds_bpermute_b32 v223, v131, v46
	ds_bpermute_b32 v224, v131, v30
	ds_bpermute_b32 v225, v131, v14
	s_waitcnt lgkmcnt(0)
	v_add_f32_e32 v114, v114, v218
	v_add_f32_e32 v110, v110, v219
	v_add_f32_e32 v94, v94, v220
	v_add_f32_e32 v78, v78, v221
	v_add_f32_e32 v62, v62, v222
	v_add_f32_e32 v46, v46, v223
	v_add_f32_e32 v30, v30, v224
	v_add_f32_e32 v14, v14, v225
	s_and_saveexec_b64 s[0:1], s[42:43]
	global_atomic_add_f32 v239, v114, s[14:15]
	global_atomic_add_f32 v239, v110, s[14:15] offset:64
	global_atomic_add_f32 v239, v94, s[14:15] offset:128
	global_atomic_add_f32 v239, v78, s[14:15] offset:192
	global_atomic_add_f32 v239, v62, s[14:15] offset:512
	global_atomic_add_f32 v239, v46, s[14:15] offset:576
	global_atomic_add_f32 v239, v30, s[14:15] offset:640
	global_atomic_add_f32 v239, v14, s[14:15] offset:704
	s_or_b64 exec, exec, s[0:1]
	s_mov_b64 s[40:41], 0
	s_mov_b64 s[0:1], 0
	s_branch .LBB0_184

; #define GAS __attribute__((address_space(1)))
; __device__ __forceinline__ u32x4 pack8(f32x4 a, f32x4 b) { u32x4 w; w.x = cvtpk(a[0], a[1]); w.y = cvtpk(a[2], a[3]); w.z = cvtpk(b[0], b[1]); w.w = cvtpk(b[2], b[3]); return w; }
; __device__ __forceinline__ f32x4 sig4(f32x4 x) { f32x4 r; r[0] = fsigmoid(x[0]); r[1] = fsigmoid(x[1]); r[2] = fsigmoid(x[2]); r[3] = fsigmoid(x[3]); return r; }
;     __device__ __forceinline__ void operator()(const f32x4 (&acc)[2][2][4][2], const Unit& u, int wr, int wc, int fr, int fq) const {
;     ...
; #pragma unroll
;             for (int ai = 0; ai < 2; ++ai)
; #pragma unroll
;                 for (int m = 0; m < 4; ++m) {
;                     const int row = rowb + ai * HALF + m * 16;
;                     float rstd = 1.f; if (mode == EM_GATE) rstd = __builtin_amdgcn_rsqf(ssq_in[row] * (1.0f / DM) + EPS);
; #pragma unroll
;                     for (int bj = 0; bj < 2; ++bj) {
;                         const size_t off = (size_t)row * DM + u.pn * BM + bj * HALF + wc * 32 + fq * 8;
;                         if (mode == EM_GATE) { *(GAS u32x4*)(o16 + off) = pack8(sig4(acc[ai][bj][m][0] * rstd), sig4(acc[ai][bj][m][1] * rstd)); }
;                         else if (mode == EM_STORE) { *(GAS u32x4*)(o16 + off) = pack8(acc[ai][bj][m][0], acc[ai][bj][m][1]); }
.Lstore_fast:
	s_lshl_b32 s0, s67, 9
	v_lshlrev_b32_e32 v238, 11, v182
	v_lshl_add_u32 v238, v176, 1, v238
	v_add_u32_e32 v238, s0, v238
	v_mov_b32_e32 v154, v238
	v_cvt_pk_bf16_f32 v130, v114, v115
	v_cvt_pk_bf16_f32 v131, v116, v117
	v_cvt_pk_bf16_f32 v132, v126, v127
	v_cvt_pk_bf16_f32 v133, v128, v129
	global_store_dwordx4 v154, v[130:133], s[18:19]
	v_cvt_pk_bf16_f32 v134, v122, v123
	v_cvt_pk_bf16_f32 v135, v124, v125
	v_cvt_pk_bf16_f32 v136, v118, v119
	v_cvt_pk_bf16_f32 v137, v120, v121
	global_store_dwordx4 v154, v[134:137], s[18:19] offset:256
	v_add_u32_e32 v154, 0x8000, v238
	v_cvt_pk_bf16_f32 v138, v110, v111
	v_cvt_pk_bf16_f32 v139, v112, v113
	v_cvt_pk_bf16_f32 v140, v102, v103
	v_cvt_pk_bf16_f32 v141, v104, v105
	global_store_dwordx4 v154, v[138:141], s[18:19]
	v_cvt_pk_bf16_f32 v142, v106, v107
	v_cvt_pk_bf16_f32 v143, v108, v109
	v_cvt_pk_bf16_f32 v144, v98, v99
	v_cvt_pk_bf16_f32 v145, v100, v101
	global_store_dwordx4 v154, v[142:145], s[18:19] offset:256
	v_add_u32_e32 v154, 0x10000, v238
	v_cvt_pk_bf16_f32 v130, v94, v95
	v_cvt_pk_bf16_f32 v131, v96, v97
	v_cvt_pk_bf16_f32 v132, v86, v87
	v_cvt_pk_bf16_f32 v133, v88, v89
	global_store_dwordx4 v154, v[130:133], s[18:19]
	v_cvt_pk_bf16_f32 v134, v90, v91
	v_cvt_pk_bf16_f32 v135, v92, v93
	v_cvt_pk_bf16_f32 v136, v82, v83
	v_cvt_pk_bf16_f32 v137, v84, v85
	global_store_dwordx4 v154, v[134:137], s[18:19] offset:256
	v_add_u32_e32 v154, 0x18000, v238
	v_cvt_pk_bf16_f32 v138, v78, v79
	v_cvt_pk_bf16_f32 v139, v80, v81
	v_cvt_pk_bf16_f32 v140, v70, v71
	v_cvt_pk_bf16_f32 v141, v72, v73
	global_store_dwordx4 v154, v[138:141], s[18:19]
	v_cvt_pk_bf16_f32 v142, v74, v75
	v_cvt_pk_bf16_f32 v143, v76, v77
	v_cvt_pk_bf16_f32 v144, v66, v67
	v_cvt_pk_bf16_f32 v145, v68, v69
	global_store_dwordx4 v154, v[142:145], s[18:19] offset:256
	v_add_u32_e32 v154, 0x40000, v238
	v_cvt_pk_bf16_f32 v130, v62, v63
	v_cvt_pk_bf16_f32 v131, v64, v65
	v_cvt_pk_bf16_f32 v132, v54, v55
	v_cvt_pk_bf16_f32 v133, v56, v57
	global_store_dwordx4 v154, v[130:133], s[18:19]
	v_cvt_pk_bf16_f32 v134, v58, v59
	v_cvt_pk_bf16_f32 v135, v60, v61
	v_cvt_pk_bf16_f32 v136, v50, v51
	v_cvt_pk_bf16_f32 v137, v52, v53
	global_store_dwordx4 v154, v[134:137], s[18:19] offset:256
	v_add_u32_e32 v154, 0x48000, v238
	v_cvt_pk_bf16_f32 v138, v46, v47
	v_cvt_pk_bf16_f32 v139, v48, v49
	v_cvt_pk_bf16_f32 v140, v38, v39
	v_cvt_pk_bf16_f32 v141, v40, v41
	global_store_dwordx4 v154, v[138:141], s[18:19]
	v_cvt_pk_bf16_f32 v142, v42, v43
	v_cvt_pk_bf16_f32 v143, v44, v45
	v_cvt_pk_bf16_f32 v144, v34, v35
	v_cvt_pk_bf16_f32 v145, v36, v37
	global_store_dwordx4 v154, v[142:145], s[18:19] offset:256
	v_add_u32_e32 v154, 0x50000, v238
	v_cvt_pk_bf16_f32 v130, v30, v31
	v_cvt_pk_bf16_f32 v131, v32, v33
	v_cvt_pk_bf16_f32 v132, v22, v23
	v_cvt_pk_bf16_f32 v133, v24, v25
	global_store_dwordx4 v154, v[130:133], s[18:19]
	v_cvt_pk_bf16_f32 v134, v26, v27
	v_cvt_pk_bf16_f32 v135, v28, v29
	v_cvt_pk_bf16_f32 v136, v18, v19
	v_cvt_pk_bf16_f32 v137, v20, v21
	global_store_dwordx4 v154, v[134:137], s[18:19] offset:256
	v_add_u32_e32 v154, 0x58000, v238
	v_cvt_pk_bf16_f32 v138, v14, v15
	v_cvt_pk_bf16_f32 v139, v16, v17
	v_cvt_pk_bf16_f32 v140, v6, v7
	v_cvt_pk_bf16_f32 v141, v8, v9
	global_store_dwordx4 v154, v[138:141], s[18:19]
	v_cvt_pk_bf16_f32 v142, v10, v11
	v_cvt_pk_bf16_f32 v143, v12, v13
	v_cvt_pk_bf16_f32 v144, v2, v3
	v_cvt_pk_bf16_f32 v145, v4, v5
	global_store_dwordx4 v154, v[142:145], s[18:19] offset:256
	s_branch .LBB0_186

; #define GAS __attribute__((address_space(1)))
; __device__ __forceinline__ u32x4 pack8(f32x4 a, f32x4 b) { u32x4 w; w.x = cvtpk(a[0], a[1]); w.y = cvtpk(a[2], a[3]); w.z = cvtpk(b[0], b[1]); w.w = cvtpk(b[2], b[3]); return w; }
; __device__ __forceinline__ f32x4 sig4(f32x4 x) { f32x4 r; r[0] = fsigmoid(x[0]); r[1] = fsigmoid(x[1]); r[2] = fsigmoid(x[2]); r[3] = fsigmoid(x[3]); return r; }
;     __device__ __forceinline__ void operator()(const f32x4 (&acc)[2][2][4][2], const Unit& u, int wr, int wc, int fr, int fq) const {
;     ...
;         } else {
; #pragma unroll
;             for (int ai = 0; ai < 2; ++ai)
; #pragma unroll
;                 for (int m = 0; m < 4; ++m) {
;                     const int row = rowb + ai * HALF + m * 16;
;                     float rstd = 1.f; if (mode == EM_GATE) rstd = __builtin_amdgcn_rsqf(ssq_in[row] * (1.0f / DM) + EPS);
; #pragma unroll
;                     for (int bj = 0; bj < 2; ++bj) {
;                         const size_t off = (size_t)row * DM + u.pn * BM + bj * HALF + wc * 32 + fq * 8;
;                         if (mode == EM_GATE) { *(GAS u32x4*)(o16 + off) = pack8(sig4(acc[ai][bj][m][0] * rstd), sig4(acc[ai][bj][m][1] * rstd)); }
;                         else if (mode == EM_STORE) { *(GAS u32x4*)(o16 + off) = pack8(acc[ai][bj][m][0], acc[ai][bj][m][1]); }
;                         else {
;                             f32x4 g0, g1; unpack8(*(const GAS u32x4*)(g16 + off), g0, g1);
;                             f32x4 v0 = g0 * acc[ai][bj][m][0], v1 = g1 * acc[ai][bj][m][1];
;                             GAS bf16_t* mf16 = (GAS bf16_t*)mf;
;                             if (flag > 0) { f32x4 a0, a1; unpack8(*(const GAS u32x4*)(mf16 + off), a0, a1); v0 += a0; v1 += a1; }
;                             if (flag < 2) *(GAS u32x4*)(mf16 + off) = pack8(v0, v1);
;                             else *(GAS u32x4*)(o16 + off) = pack8(v0, v1);
;                         }
.LBB0_555:
	s_cmp_eq_u32 s35, 4
	s_cbranch_scc1 .Lmerge_fast
	s_branch .Lstore_fast

; #define PG8_WAIT_V(n) asm volatile("s_waitcnt vmcnt(" #n ")" ::: "memory")
; #define PG8_BAR __builtin_amdgcn_s_barrier()
; __device__ __forceinline__ void gemm_phase(LAS unsigned char* lds, const Gemm g, const StaticOrder& S, const Epi& E) {
;     ...
;         cur = nxt; cA = nA; cB = nB; ++ui;
;         if (wr == 1) PG8_BAR;
;     }
;     PG8_WAIT_V(0);
;     PG8_BAR;
.LBB0_712:
	v_readlane_b32 s0, v246, 50
	v_readlane_b32 s1, v246, 51
	s_andn2_b64 vcc, exec, s[0:1]
	s_cbranch_vccnz .LBB0_169
	s_barrier
	s_branch .LBB0_169
.LBB0_763:
	s_waitcnt vmcnt(0)
	v_readlane_b32 s42, v246, 7
	s_mov_b32 s71, s69
	v_readlane_b32 s43, v246, 8
	s_movk_i32 s72, 0x100
	v_readlane_b32 s37, v246, 41
	s_barrier
